# x2 (G_MLPOUT result) written privately lane-linear over x1's workspace slot and read there by G_PLE; d_out only gets the final output; PP moved to dead HID region
# speedup vs baseline: 1.0272x; 1.0075x over previous
;     __device__ __forceinline__ void load_row(RowIn& R, size_t off) const {
; #pragma unroll
;         for (int bj = 0; bj < 2; ++bj)
; #pragma unroll
;             for (int n = 0; n < 2; ++n) { const size_t o = off + bj * HALF + n * 16; R.b[bj][n] = *(const f32x4*)(res + o); if (MODE == 1) R.pw[bj][n] = *(const u32x2*)(PP + o); }
;     }
;     __device__ __forceinline__ void operator()(const typename AccT<I8>::type (&acc)[2][2][4][2], const Unit& u, int wr, int wc, int fr, int fq) const {
;         const int row0 = u.pm * BM + wr * 64 + fr, col0 = u.pn * BM + wc * 32 + 4 * fq;
;         f32x4 sv[2][2];
;         if (I8) {
; #pragma unroll
;             for (int bj = 0; bj < 2; ++bj)
; #pragma unroll
;                 for (int n = 0; n < 2; ++n) sv[bj][n] = *(const f32x4*)(swc + col0 + bj * HALF + n * 16);
;         }
;         float rsv[8];
; #pragma unroll
;         for (int s = 0; s < 8; ++s) { const int r = row0 + (s >> 2) * HALF + (s & 3) * 16; float rs = 1.f; if (MODE == 1) rs = __builtin_amdgcn_rsqf(rstd[r] * (1.0f / 4096.0f) + 1e-6f); if (I8) rs *= sxr[r]; rsv[s] = rs; }
;         RowIn cur, nxt;
;         load_row(cur, (size_t)row0 * 4096 + col0);
; #pragma unroll
;         for (int s = 0; s < 8; ++s) { const int ai = s >> 2, m = s & 3; const int r = row0 + ai * HALF + m * 16; const size_t off = (size_t)r * 4096 + col0;
;                 if (s + 1 < 8) load_row(nxt, (size_t)(row0 + ((s + 1) >> 2) * HALF + ((s + 1) & 3) * 16) * 4096 + col0);
;                 const float rs = rsv[s];
;                 float ss = 0.f, mx = 0.f;
; #pragma unroll
;                 for (int bj = 0; bj < 2; ++bj)
; #pragma unroll
;                     for (int n = 0; n < 2; ++n) { const size_t o = off + bj * HALF + n * 16; const f32x4 b = cur.b[bj][n]; f32x4 v;
;                         if constexpr (I8) v = __builtin_convertvector(acc[ai][bj][m][n], f32x4) * rs * sv[bj][n]; else v = acc[ai][bj][m][n];
;                         if (MODE == 1) { const u32x2 pw = cur.pw[bj][n]; const f32x4 pp = (f32x4){bf_lo(pw.x), bf_hi(pw.x), bf_lo(pw.y), bf_hi(pw.y)}; v = sig4(I8 ? v : v * rs) * pp; }
;                         const f32x4 x = b + v; *(f32x4*)(out + o) = x;
;                         if (MODE == 0 && XB) { u32x2 w; w.x = cvt_pk_bf16(x[0], x[1]); w.y = cvt_pk_bf16(x[2], x[3]); *(u32x2*)(XB + o) = w; ss += (x[0] * x[0] + x[1] * x[1]) + (x[2] * x[2] + x[3] * x[3]);
.LBB0_2095:
	s_lshl_b32 s98, s6, 4
	s_add_i32 s98, s98, s2
	s_sub_i32 s99, s98, 888
	s_cmp_lt_u32 s98, 888
	s_cselect_b32 s98, s98, s99
	s_mov_b32 s99, 0x4200000
	s_cselect_b32 s99, 0x3f600000, s99
	s_lshl_b32 s98, s98, 18
	s_add_u32 s98, s98, s99
	v_and_b32_e32 v250, 63, v0
	v_lshlrev_b32_e32 v250, 4, v250
	v_lshrrev_b32_e32 v251, 6, v0
	v_lshl_add_u32 v250, v251, 15, v250
	v_add_u32_e32 v250, s98, v250
	v_mov_b32_e32 v251, 0
	v_lshl_add_u64 v[250:251], s[96:97], 0, v[250:251]
	v_mov_b32_e32 v130, v0
	v_readlane_b32 s52, v254, 8
	v_ashrrev_i32_e32 v131, 2, v130
	v_and_b32_e32 v131, 0xffffffc0, v131
	v_lshl_add_u32 v131, s6, 8, v131
	v_bfe_u32 v162, v130, 4, 2
	v_and_or_b32 v184, v130, 15, v131
	v_lshrrev_b32_e32 v130, 1, v130
	v_and_b32_e32 v130, 0x60, v130
	v_lshl_or_b32 v130, s2, 8, v130
	v_lshl_or_b32 v182, v162, 2, v130
	v_ashrrev_i32_e32 v185, 31, v184
	v_readlane_b32 s58, v254, 14
	v_readlane_b32 s59, v254, 15
	v_ashrrev_i32_e32 v183, 31, v182
	v_lshlrev_b64 v[130:131], 14, v[184:185]
	s_mov_b64 s[6:7], s[58:59]
	v_or_b32_e32 v188, 16, v184
	v_lshl_add_u64 v[130:131], s[6:7], 0, v[130:131]
	v_lshlrev_b64 v[132:133], 2, v[182:183]
	v_ashrrev_i32_e32 v189, 31, v188
	s_mov_b64 s[98:99], 0x0
	v_lshl_add_u64 v[190:191], v[250:251], 0, s[98:99]
	v_lshlrev_b64 v[130:131], 14, v[188:189]
	v_lshl_add_u64 v[130:131], s[6:7], 0, v[130:131]
	s_mov_b64 s[98:99], 0x1000
	v_lshl_add_u64 v[186:187], v[250:251], 0, s[98:99]
	s_mov_b64 s[98:99], 0x0
	v_lshl_add_u64 v[252:253], v[250:251], 0, s[98:99]
	global_load_dwordx4 v[158:161], v[252:253], off
	global_load_dwordx4 v[154:157], v[252:253], off offset:1024
	global_load_dwordx4 v[150:153], v[252:253], off offset:2048
	global_load_dwordx4 v[146:149], v[252:253], off offset:3072
	s_mov_b64 s[98:99], 0x1000
	v_lshl_add_u64 v[252:253], v[250:251], 0, s[98:99]
	global_load_dwordx4 v[142:145], v[252:253], off
	global_load_dwordx4 v[138:141], v[252:253], off offset:1024
	global_load_dwordx4 v[134:137], v[252:253], off offset:2048
	global_load_dwordx4 v[130:133], v[252:253], off offset:3072
	v_cndmask_b32_e64 v163, 0, 1, s[18:19]
	v_cmp_ne_u32_e64 s[8:9], 1, v163
	s_andn2_b64 vcc, exec, s[18:19]
	v_cmp_eq_u32_e64 s[6:7], 0, v162
	v_readlane_b32 s53, v254, 9
	v_readlane_b32 s54, v254, 10
	v_readlane_b32 s55, v254, 11
	v_readlane_b32 s56, v254, 12
	v_readlane_b32 s57, v254, 13
	s_waitcnt vmcnt(0)
	v_pk_add_f32 v[168:169], v[128:129], v[160:161]
	v_pk_add_f32 v[166:167], v[126:127], v[158:159]
	v_pk_add_f32 v[162:163], v[122:123], v[154:155]
	v_pk_add_f32 v[158:159], v[118:119], v[150:151]
	v_pk_add_f32 v[126:127], v[114:115], v[146:147]
	global_store_dwordx4 v[190:191], v[166:169], off
	s_cbranch_vccnz .LBB0_2154
	v_lshlrev_b64 v[114:115], 12, v[184:185]
	v_lshl_add_u64 v[114:115], v[114:115], 0, v[182:183]
	v_readlane_b32 s2, v254, 40
	v_lshlrev_b64 v[122:123], 1, v[114:115]
	v_readlane_b32 s3, v254, 41
	s_nop 0
	v_cvt_pk_bf16_f32 v118, v166, v167
	s_nop 0
	v_cvt_pk_bf16_f32 v119, v168, v169
	v_pk_add_f32 v[164:165], v[124:125], v[156:157]
	v_pk_add_f32 v[160:161], v[120:121], v[152:153]
	v_lshl_add_u64 v[114:115], s[2:3], 0, v[122:123]
	global_store_dwordx2 v[114:115], v[118:119], off
	v_mul_f32_e32 v114, v167, v167
	v_mul_f32_e32 v115, v169, v169
	v_fmac_f32_e32 v114, v166, v166
	v_fmac_f32_e32 v115, v168, v168
	v_or_b32_e32 v118, 32, v122
	v_mov_b32_e32 v119, v123
	v_add_f32_e32 v128, v114, v115
	global_store_dwordx4 v[190:191], v[162:165], off offset:1024
	s_nop 0
	v_cvt_pk_bf16_f32 v114, v162, v163
	s_nop 0
	v_cvt_pk_bf16_f32 v115, v164, v165
	v_lshl_add_u64 v[118:119], s[2:3], 0, v[118:119]
	global_store_dwordx2 v[118:119], v[114:115], off
	v_mul_f32_e32 v114, v163, v163
	v_mul_f32_e32 v115, v165, v165
	v_fmac_f32_e32 v114, v162, v162
	v_fmac_f32_e32 v115, v164, v164
	v_add_f32_e32 v114, v114, v115
	v_add_f32_e32 v114, v128, v114
	v_mul_f32_e32 v115, v159, v159
	v_mul_f32_e32 v128, v161, v161
	v_fmac_f32_e32 v115, v158, v158
	v_fmac_f32_e32 v128, v160, v160
	v_add_f32_e32 v115, v115, v128
	v_pk_add_f32 v[128:129], v[116:117], v[148:149]
	v_add_f32_e32 v114, v114, v115
	v_mul_f32_e32 v115, v127, v127
	v_mul_f32_e32 v150, v129, v129
	v_fmac_f32_e32 v115, v126, v126
	v_fmac_f32_e32 v150, v128, v128
	v_add_f32_e32 v115, v115, v150
	v_and_b32_e32 v150, 64, v195
	v_add_f32_e32 v115, v114, v115
	v_xor_b32_e32 v114, 16, v195
	v_add_u32_e32 v150, 64, v150
	v_cmp_lt_i32_e32 vcc, v114, v150
	v_or_b32_e32 v146, 0x100, v122
	v_mov_b32_e32 v147, v123
	v_cndmask_b32_e32 v114, v195, v114, vcc
	v_lshlrev_b32_e32 v114, 2, v114
	ds_bpermute_b32 v151, v114, v115
	global_store_dwordx4 v[190:191], v[158:161], off offset:2048
	s_nop 0
	v_cvt_pk_bf16_f32 v118, v158, v159
	s_nop 0
	v_cvt_pk_bf16_f32 v119, v160, v161
	v_lshl_add_u64 v[146:147], s[2:3], 0, v[146:147]
	global_store_dwordx2 v[146:147], v[118:119], off
	global_store_dwordx4 v[190:191], v[126:129], off offset:3072
	s_waitcnt lgkmcnt(0)
	v_add_f32_e32 v118, v115, v151
	v_xor_b32_e32 v115, 32, v195
	v_cmp_lt_i32_e32 vcc, v115, v150
	v_or_b32_e32 v122, 0x120, v122
	v_lshl_add_u64 v[122:123], s[2:3], 0, v[122:123]
	v_cndmask_b32_e32 v115, v195, v115, vcc
	v_lshlrev_b32_e32 v115, 2, v115
	ds_bpermute_b32 v119, v115, v118
	s_nop 0
	v_cvt_pk_bf16_f32 v146, v126, v127
	s_nop 0
	v_cvt_pk_bf16_f32 v147, v128, v129
	global_store_dwordx2 v[122:123], v[146:147], off
	s_and_saveexec_b64 s[2:3], s[6:7]
	s_cbranch_execz .LBB0_2098
	v_lshl_add_u64 v[122:123], v[184:185], 2, s[10:11]
	s_waitcnt lgkmcnt(0)
	v_add_f32_e32 v118, v118, v119
	global_atomic_add_f32 v[122:123], v118, off

;     __device__ __forceinline__ void load_row(RowIn& R, size_t off) const {
; #pragma unroll
;         for (int bj = 0; bj < 2; ++bj)
; #pragma unroll
;             for (int n = 0; n < 2; ++n) { const size_t o = off + bj * HALF + n * 16; R.b[bj][n] = *(const f32x4*)(res + o); if (MODE == 1) R.pw[bj][n] = *(const u32x2*)(PP + o); }
;     }
;     __device__ __forceinline__ void operator()(const typename AccT<I8>::type (&acc)[2][2][4][2], const Unit& u, int wr, int wc, int fr, int fq) const {
;         const int row0 = u.pm * BM + wr * 64 + fr, col0 = u.pn * BM + wc * 32 + 4 * fq;
;         f32x4 sv[2][2];
;         if (I8) {
; #pragma unroll
;             for (int bj = 0; bj < 2; ++bj)
; #pragma unroll
;                 for (int n = 0; n < 2; ++n) sv[bj][n] = *(const f32x4*)(swc + col0 + bj * HALF + n * 16);
;         }
;         float rsv[8];
; #pragma unroll
;         for (int s = 0; s < 8; ++s) { const int r = row0 + (s >> 2) * HALF + (s & 3) * 16; float rs = 1.f; if (MODE == 1) rs = __builtin_amdgcn_rsqf(rstd[r] * (1.0f / 4096.0f) + 1e-6f); if (I8) rs *= sxr[r]; rsv[s] = rs; }
;         RowIn cur, nxt;
;         load_row(cur, (size_t)row0 * 4096 + col0);
; #pragma unroll
;         for (int s = 0; s < 8; ++s) { const int ai = s >> 2, m = s & 3; const int r = row0 + ai * HALF + m * 16; const size_t off = (size_t)r * 4096 + col0;
;                 if (s + 1 < 8) load_row(nxt, (size_t)(row0 + ((s + 1) >> 2) * HALF + ((s + 1) & 3) * 16) * 4096 + col0);
;                 const float rs = rsv[s];
;                 float ss = 0.f, mx = 0.f;
; #pragma unroll
;                 for (int bj = 0; bj < 2; ++bj)
; #pragma unroll
;                     for (int n = 0; n < 2; ++n) { const size_t o = off + bj * HALF + n * 16; const f32x4 b = cur.b[bj][n]; f32x4 v;
;                         if constexpr (I8) v = __builtin_convertvector(acc[ai][bj][m][n], f32x4) * rs * sv[bj][n]; else v = acc[ai][bj][m][n];
;                         if (MODE == 1) { const u32x2 pw = cur.pw[bj][n]; const f32x4 pp = (f32x4){bf_lo(pw.x), bf_hi(pw.x), bf_lo(pw.y), bf_hi(pw.y)}; v = sig4(I8 ? v : v * rs) * pp; }
;                         const f32x4 x = b + v; *(f32x4*)(out + o) = x;
;                         if (MODE == 0 && XB) { u32x2 w; w.x = cvt_pk_bf16(x[0], x[1]); w.y = cvt_pk_bf16(x[2], x[3]); *(u32x2*)(XB + o) = w; ss += (x[0] * x[0] + x[1] * x[1]) + (x[2] * x[2] + x[3] * x[3]);
.LBB0_2101:
	v_pk_add_f32 v[164:165], v[124:125], v[156:157]
	v_pk_add_f32 v[160:161], v[120:121], v[152:153]
	v_pk_add_f32 v[128:129], v[116:117], v[148:149]
	global_store_dwordx4 v[190:191], v[162:165], off offset:1024
	global_store_dwordx4 v[190:191], v[158:161], off offset:2048
	global_store_dwordx4 v[190:191], v[126:129], off offset:3072
.LBB0_2102:
	v_or_b32_e32 v156, 32, v184
	v_ashrrev_i32_e32 v157, 31, v156
	v_readlane_b32 s52, v254, 8
	s_waitcnt lgkmcnt(0)
	v_lshlrev_b64 v[114:115], 14, v[156:157]
	v_readlane_b32 s58, v254, 14
	v_readlane_b32 s59, v254, 15
	v_pk_add_f32 v[152:153], v[112:113], v[144:145]
	v_pk_add_f32 v[150:151], v[110:111], v[142:143]
	v_lshl_add_u64 v[114:115], s[58:59], 0, v[114:115]
	s_mov_b64 s[98:99], 0x2000
	v_lshl_add_u64 v[154:155], v[250:251], 0, s[98:99]
	s_mov_b64 s[98:99], 0x2000
	v_lshl_add_u64 v[252:253], v[250:251], 0, s[98:99]
	global_load_dwordx4 v[126:129], v[252:253], off
	global_load_dwordx4 v[122:125], v[252:253], off offset:1024
	global_load_dwordx4 v[118:121], v[252:253], off offset:2048
	global_load_dwordx4 v[114:117], v[252:253], off offset:3072
	s_and_b64 vcc, exec, s[8:9]
	v_pk_add_f32 v[146:147], v[106:107], v[138:139]
	v_pk_add_f32 v[142:143], v[102:103], v[134:135]
	v_pk_add_f32 v[110:111], v[98:99], v[130:131]
	v_readlane_b32 s53, v254, 9
	v_readlane_b32 s54, v254, 10
	v_readlane_b32 s55, v254, 11
	v_readlane_b32 s56, v254, 12
	v_readlane_b32 s57, v254, 13
	global_store_dwordx4 v[186:187], v[150:153], off
	s_cbranch_vccnz .LBB0_2155
	v_lshlrev_b64 v[98:99], 12, v[188:189]
	v_lshl_add_u64 v[98:99], v[98:99], 0, v[182:183]
	v_readlane_b32 s2, v254, 40
	v_lshlrev_b64 v[106:107], 1, v[98:99]
	v_readlane_b32 s3, v254, 41
	s_nop 0
	v_cvt_pk_bf16_f32 v102, v150, v151
	s_nop 0
	v_cvt_pk_bf16_f32 v103, v152, v153
	v_pk_add_f32 v[148:149], v[108:109], v[140:141]
	v_pk_add_f32 v[144:145], v[104:105], v[136:137]
	v_lshl_add_u64 v[98:99], s[2:3], 0, v[106:107]
	global_store_dwordx2 v[98:99], v[102:103], off
	v_mul_f32_e32 v98, v151, v151
	v_mul_f32_e32 v99, v153, v153
	v_fmac_f32_e32 v98, v150, v150
	v_fmac_f32_e32 v99, v152, v152
	v_or_b32_e32 v102, 32, v106
	v_mov_b32_e32 v103, v107
	v_add_f32_e32 v112, v98, v99
	global_store_dwordx4 v[186:187], v[146:149], off offset:1024
	s_nop 0
	v_cvt_pk_bf16_f32 v98, v146, v147
	s_nop 0
	v_cvt_pk_bf16_f32 v99, v148, v149
	v_lshl_add_u64 v[102:103], s[2:3], 0, v[102:103]
	global_store_dwordx2 v[102:103], v[98:99], off
	v_mul_f32_e32 v98, v147, v147
	v_mul_f32_e32 v99, v149, v149
	v_fmac_f32_e32 v98, v146, v146
	v_fmac_f32_e32 v99, v148, v148
	v_add_f32_e32 v98, v98, v99
	v_add_f32_e32 v98, v112, v98
	v_mul_f32_e32 v99, v143, v143
	v_mul_f32_e32 v112, v145, v145
	v_fmac_f32_e32 v99, v142, v142
	v_fmac_f32_e32 v112, v144, v144
	v_add_f32_e32 v99, v99, v112
	v_pk_add_f32 v[112:113], v[100:101], v[132:133]
	v_add_f32_e32 v98, v98, v99
	v_mul_f32_e32 v99, v111, v111
	v_mul_f32_e32 v134, v113, v113
	v_fmac_f32_e32 v99, v110, v110
	v_fmac_f32_e32 v134, v112, v112
	v_add_f32_e32 v99, v99, v134
	v_and_b32_e32 v134, 64, v195
	v_add_f32_e32 v99, v98, v99
	v_xor_b32_e32 v98, 16, v195
	v_add_u32_e32 v134, 64, v134
	v_cmp_lt_i32_e32 vcc, v98, v134
	v_or_b32_e32 v130, 0x100, v106
	v_mov_b32_e32 v131, v107
	v_cndmask_b32_e32 v98, v195, v98, vcc
	v_lshlrev_b32_e32 v98, 2, v98
	ds_bpermute_b32 v135, v98, v99
	global_store_dwordx4 v[186:187], v[142:145], off offset:2048
	s_nop 0
	v_cvt_pk_bf16_f32 v102, v142, v143
	s_nop 0
	v_cvt_pk_bf16_f32 v103, v144, v145
	v_lshl_add_u64 v[130:131], s[2:3], 0, v[130:131]
	global_store_dwordx2 v[130:131], v[102:103], off
	global_store_dwordx4 v[186:187], v[110:113], off offset:3072
	s_waitcnt lgkmcnt(0)
	v_add_f32_e32 v102, v99, v135
	v_xor_b32_e32 v99, 32, v195
	v_cmp_lt_i32_e32 vcc, v99, v134
	v_or_b32_e32 v106, 0x120, v106
	v_lshl_add_u64 v[106:107], s[2:3], 0, v[106:107]
	v_cndmask_b32_e32 v99, v195, v99, vcc
	v_lshlrev_b32_e32 v99, 2, v99
	ds_bpermute_b32 v103, v99, v102
	s_nop 0
	v_cvt_pk_bf16_f32 v130, v110, v111
	s_nop 0
	v_cvt_pk_bf16_f32 v131, v112, v113
	global_store_dwordx2 v[106:107], v[130:131], off
	s_and_saveexec_b64 s[2:3], s[6:7]
	s_cbranch_execz .LBB0_2105
	v_lshl_add_u64 v[106:107], v[188:189], 2, s[10:11]
	s_waitcnt lgkmcnt(0)
	v_add_f32_e32 v102, v102, v103
	global_atomic_add_f32 v[106:107], v102, off

;     __device__ __forceinline__ void load_row(RowIn& R, size_t off) const {
; #pragma unroll
;         for (int bj = 0; bj < 2; ++bj)
; #pragma unroll
;             for (int n = 0; n < 2; ++n) { const size_t o = off + bj * HALF + n * 16; R.b[bj][n] = *(const f32x4*)(res + o); if (MODE == 1) R.pw[bj][n] = *(const u32x2*)(PP + o); }
;     }
;     __device__ __forceinline__ void operator()(const typename AccT<I8>::type (&acc)[2][2][4][2], const Unit& u, int wr, int wc, int fr, int fq) const {
;         const int row0 = u.pm * BM + wr * 64 + fr, col0 = u.pn * BM + wc * 32 + 4 * fq;
;         f32x4 sv[2][2];
;         if (I8) {
; #pragma unroll
;             for (int bj = 0; bj < 2; ++bj)
; #pragma unroll
;                 for (int n = 0; n < 2; ++n) sv[bj][n] = *(const f32x4*)(swc + col0 + bj * HALF + n * 16);
;         }
;         float rsv[8];
; #pragma unroll
;         for (int s = 0; s < 8; ++s) { const int r = row0 + (s >> 2) * HALF + (s & 3) * 16; float rs = 1.f; if (MODE == 1) rs = __builtin_amdgcn_rsqf(rstd[r] * (1.0f / 4096.0f) + 1e-6f); if (I8) rs *= sxr[r]; rsv[s] = rs; }
;         RowIn cur, nxt;
;         load_row(cur, (size_t)row0 * 4096 + col0);
; #pragma unroll
;         for (int s = 0; s < 8; ++s) { const int ai = s >> 2, m = s & 3; const int r = row0 + ai * HALF + m * 16; const size_t off = (size_t)r * 4096 + col0;
;                 if (s + 1 < 8) load_row(nxt, (size_t)(row0 + ((s + 1) >> 2) * HALF + ((s + 1) & 3) * 16) * 4096 + col0);
;                 const float rs = rsv[s];
;                 float ss = 0.f, mx = 0.f;
; #pragma unroll
;                 for (int bj = 0; bj < 2; ++bj)
; #pragma unroll
;                     for (int n = 0; n < 2; ++n) { const size_t o = off + bj * HALF + n * 16; const f32x4 b = cur.b[bj][n]; f32x4 v;
;                         if constexpr (I8) v = __builtin_convertvector(acc[ai][bj][m][n], f32x4) * rs * sv[bj][n]; else v = acc[ai][bj][m][n];
;                         if (MODE == 1) { const u32x2 pw = cur.pw[bj][n]; const f32x4 pp = (f32x4){bf_lo(pw.x), bf_hi(pw.x), bf_lo(pw.y), bf_hi(pw.y)}; v = sig4(I8 ? v : v * rs) * pp; }
;                         const f32x4 x = b + v; *(f32x4*)(out + o) = x;
;                         if (MODE == 0 && XB) { u32x2 w; w.x = cvt_pk_bf16(x[0], x[1]); w.y = cvt_pk_bf16(x[2], x[3]); *(u32x2*)(XB + o) = w; ss += (x[0] * x[0] + x[1] * x[1]) + (x[2] * x[2] + x[3] * x[3]);
.LBB0_2108:
	v_pk_add_f32 v[148:149], v[108:109], v[140:141]
	v_pk_add_f32 v[144:145], v[104:105], v[136:137]
	v_pk_add_f32 v[112:113], v[100:101], v[132:133]
	global_store_dwordx4 v[186:187], v[146:149], off offset:1024
	global_store_dwordx4 v[186:187], v[142:145], off offset:2048
	global_store_dwordx4 v[186:187], v[110:113], off offset:3072
.LBB0_2109:
	v_or_b32_e32 v140, 48, v184
	v_ashrrev_i32_e32 v141, 31, v140
	v_readlane_b32 s52, v254, 8
	s_waitcnt lgkmcnt(0)
	v_lshlrev_b64 v[98:99], 14, v[140:141]
	v_readlane_b32 s58, v254, 14
	v_readlane_b32 s59, v254, 15
	s_waitcnt vmcnt(4)
	v_pk_add_f32 v[136:137], v[96:97], v[128:129]
	v_pk_add_f32 v[134:135], v[94:95], v[126:127]
	v_lshl_add_u64 v[98:99], s[58:59], 0, v[98:99]
	s_mov_b64 s[98:99], 0x3000
	v_lshl_add_u64 v[138:139], v[250:251], 0, s[98:99]
	s_mov_b64 s[98:99], 0x3000
	v_lshl_add_u64 v[252:253], v[250:251], 0, s[98:99]
	global_load_dwordx4 v[110:113], v[252:253], off
	global_load_dwordx4 v[106:109], v[252:253], off offset:1024
	global_load_dwordx4 v[102:105], v[252:253], off offset:2048
	global_load_dwordx4 v[98:101], v[252:253], off offset:3072
	s_and_b64 vcc, exec, s[8:9]
	s_waitcnt vmcnt(7)
	v_pk_add_f32 v[130:131], v[90:91], v[122:123]
	s_waitcnt vmcnt(6)
	v_pk_add_f32 v[126:127], v[86:87], v[118:119]
	s_waitcnt vmcnt(5)
	v_pk_add_f32 v[94:95], v[82:83], v[114:115]
	v_readlane_b32 s53, v254, 9
	v_readlane_b32 s54, v254, 10
	v_readlane_b32 s55, v254, 11
	v_readlane_b32 s56, v254, 12
	v_readlane_b32 s57, v254, 13
	global_store_dwordx4 v[154:155], v[134:137], off
	s_cbranch_vccnz .LBB0_2156
	v_lshlrev_b64 v[82:83], 12, v[156:157]
	v_lshl_add_u64 v[82:83], v[82:83], 0, v[182:183]
	v_readlane_b32 s2, v254, 40
	v_lshlrev_b64 v[90:91], 1, v[82:83]
	v_readlane_b32 s3, v254, 41
	s_nop 0
	v_cvt_pk_bf16_f32 v86, v134, v135
	s_nop 0
	v_cvt_pk_bf16_f32 v87, v136, v137
	v_pk_add_f32 v[132:133], v[92:93], v[124:125]
	v_pk_add_f32 v[128:129], v[88:89], v[120:121]
	v_lshl_add_u64 v[82:83], s[2:3], 0, v[90:91]
	global_store_dwordx2 v[82:83], v[86:87], off
	v_mul_f32_e32 v82, v135, v135
	v_mul_f32_e32 v83, v137, v137
	v_fmac_f32_e32 v82, v134, v134
	v_fmac_f32_e32 v83, v136, v136
	v_or_b32_e32 v86, 32, v90
	v_mov_b32_e32 v87, v91
	v_add_f32_e32 v96, v82, v83
	global_store_dwordx4 v[154:155], v[130:133], off offset:1024
	s_nop 0
	v_cvt_pk_bf16_f32 v82, v130, v131
	s_nop 0
	v_cvt_pk_bf16_f32 v83, v132, v133
	v_lshl_add_u64 v[86:87], s[2:3], 0, v[86:87]
	global_store_dwordx2 v[86:87], v[82:83], off
	v_mul_f32_e32 v82, v131, v131
	v_mul_f32_e32 v83, v133, v133
	v_fmac_f32_e32 v82, v130, v130
	v_fmac_f32_e32 v83, v132, v132
	v_add_f32_e32 v82, v82, v83
	v_add_f32_e32 v82, v96, v82
	v_mul_f32_e32 v83, v127, v127
	v_mul_f32_e32 v96, v129, v129
	v_fmac_f32_e32 v83, v126, v126
	v_fmac_f32_e32 v96, v128, v128
	v_add_f32_e32 v83, v83, v96
	v_pk_add_f32 v[96:97], v[84:85], v[116:117]
	v_add_f32_e32 v82, v82, v83
	v_mul_f32_e32 v83, v95, v95
	v_mul_f32_e32 v118, v97, v97
	v_fmac_f32_e32 v83, v94, v94
	v_fmac_f32_e32 v118, v96, v96
	v_add_f32_e32 v83, v83, v118
	v_and_b32_e32 v118, 64, v195
	v_add_f32_e32 v83, v82, v83
	v_xor_b32_e32 v82, 16, v195
	v_add_u32_e32 v118, 64, v118
	v_cmp_lt_i32_e32 vcc, v82, v118
	v_or_b32_e32 v114, 0x100, v90
	v_mov_b32_e32 v115, v91
	v_cndmask_b32_e32 v82, v195, v82, vcc
	v_lshlrev_b32_e32 v82, 2, v82
	ds_bpermute_b32 v119, v82, v83
	global_store_dwordx4 v[154:155], v[126:129], off offset:2048
	s_nop 0
	v_cvt_pk_bf16_f32 v86, v126, v127
	s_nop 0
	v_cvt_pk_bf16_f32 v87, v128, v129
	v_lshl_add_u64 v[114:115], s[2:3], 0, v[114:115]
	global_store_dwordx2 v[114:115], v[86:87], off
	global_store_dwordx4 v[154:155], v[94:97], off offset:3072
	s_waitcnt lgkmcnt(0)
	v_add_f32_e32 v86, v83, v119
	v_xor_b32_e32 v83, 32, v195
	v_cmp_lt_i32_e32 vcc, v83, v118
	v_or_b32_e32 v90, 0x120, v90
	v_lshl_add_u64 v[90:91], s[2:3], 0, v[90:91]
	v_cndmask_b32_e32 v83, v195, v83, vcc
	v_lshlrev_b32_e32 v83, 2, v83
	ds_bpermute_b32 v87, v83, v86
	s_nop 0
	v_cvt_pk_bf16_f32 v114, v94, v95
	s_nop 0
	v_cvt_pk_bf16_f32 v115, v96, v97
	global_store_dwordx2 v[90:91], v[114:115], off
	s_and_saveexec_b64 s[2:3], s[6:7]
	s_cbranch_execz .LBB0_2112
	v_lshl_add_u64 v[90:91], v[156:157], 2, s[10:11]
	s_waitcnt lgkmcnt(0)
	v_add_f32_e32 v86, v86, v87
	global_atomic_add_f32 v[90:91], v86, off

;     __device__ __forceinline__ void load_row(RowIn& R, size_t off) const {
; #pragma unroll
;         for (int bj = 0; bj < 2; ++bj)
; #pragma unroll
;             for (int n = 0; n < 2; ++n) { const size_t o = off + bj * HALF + n * 16; R.b[bj][n] = *(const f32x4*)(res + o); if (MODE == 1) R.pw[bj][n] = *(const u32x2*)(PP + o); }
;     }
;     __device__ __forceinline__ void operator()(const typename AccT<I8>::type (&acc)[2][2][4][2], const Unit& u, int wr, int wc, int fr, int fq) const {
;         const int row0 = u.pm * BM + wr * 64 + fr, col0 = u.pn * BM + wc * 32 + 4 * fq;
;         f32x4 sv[2][2];
;         if (I8) {
; #pragma unroll
;             for (int bj = 0; bj < 2; ++bj)
; #pragma unroll
;                 for (int n = 0; n < 2; ++n) sv[bj][n] = *(const f32x4*)(swc + col0 + bj * HALF + n * 16);
;         }
;         float rsv[8];
; #pragma unroll
;         for (int s = 0; s < 8; ++s) { const int r = row0 + (s >> 2) * HALF + (s & 3) * 16; float rs = 1.f; if (MODE == 1) rs = __builtin_amdgcn_rsqf(rstd[r] * (1.0f / 4096.0f) + 1e-6f); if (I8) rs *= sxr[r]; rsv[s] = rs; }
;         RowIn cur, nxt;
;         load_row(cur, (size_t)row0 * 4096 + col0);
; #pragma unroll
;         for (int s = 0; s < 8; ++s) { const int ai = s >> 2, m = s & 3; const int r = row0 + ai * HALF + m * 16; const size_t off = (size_t)r * 4096 + col0;
;                 if (s + 1 < 8) load_row(nxt, (size_t)(row0 + ((s + 1) >> 2) * HALF + ((s + 1) & 3) * 16) * 4096 + col0);
;                 const float rs = rsv[s];
;                 float ss = 0.f, mx = 0.f;
; #pragma unroll
;                 for (int bj = 0; bj < 2; ++bj)
; #pragma unroll
;                     for (int n = 0; n < 2; ++n) { const size_t o = off + bj * HALF + n * 16; const f32x4 b = cur.b[bj][n]; f32x4 v;
;                         if constexpr (I8) v = __builtin_convertvector(acc[ai][bj][m][n], f32x4) * rs * sv[bj][n]; else v = acc[ai][bj][m][n];
;                         if (MODE == 1) { const u32x2 pw = cur.pw[bj][n]; const f32x4 pp = (f32x4){bf_lo(pw.x), bf_hi(pw.x), bf_lo(pw.y), bf_hi(pw.y)}; v = sig4(I8 ? v : v * rs) * pp; }
;                         const f32x4 x = b + v; *(f32x4*)(out + o) = x;
;                         if (MODE == 0 && XB) { u32x2 w; w.x = cvt_pk_bf16(x[0], x[1]); w.y = cvt_pk_bf16(x[2], x[3]); *(u32x2*)(XB + o) = w; ss += (x[0] * x[0] + x[1] * x[1]) + (x[2] * x[2] + x[3] * x[3]);
.LBB0_2115:
	v_pk_add_f32 v[132:133], v[92:93], v[124:125]
	v_pk_add_f32 v[128:129], v[88:89], v[120:121]
	v_pk_add_f32 v[96:97], v[84:85], v[116:117]
	global_store_dwordx4 v[154:155], v[130:133], off offset:1024
	global_store_dwordx4 v[154:155], v[126:129], off offset:2048
	global_store_dwordx4 v[154:155], v[94:97], off offset:3072
.LBB0_2116:
	v_add_u32_e32 v122, 0x80, v184
	v_ashrrev_i32_e32 v123, 31, v122
	v_readlane_b32 s52, v254, 8
	s_waitcnt lgkmcnt(0)
	v_lshlrev_b64 v[82:83], 14, v[122:123]
	v_readlane_b32 s58, v254, 14
	v_readlane_b32 s59, v254, 15
	s_waitcnt vmcnt(4)
	v_pk_add_f32 v[120:121], v[80:81], v[112:113]
	v_pk_add_f32 v[118:119], v[78:79], v[110:111]
	v_lshl_add_u64 v[82:83], s[58:59], 0, v[82:83]
	s_mov_b64 s[98:99], 0x4000
	v_lshl_add_u64 v[124:125], v[250:251], 0, s[98:99]
	s_mov_b64 s[98:99], 0x4000
	v_lshl_add_u64 v[252:253], v[250:251], 0, s[98:99]
	global_load_dwordx4 v[94:97], v[252:253], off
	global_load_dwordx4 v[90:93], v[252:253], off offset:1024
	global_load_dwordx4 v[86:89], v[252:253], off offset:2048
	global_load_dwordx4 v[82:85], v[252:253], off offset:3072
	s_and_b64 vcc, exec, s[8:9]
	s_waitcnt vmcnt(7)
	v_pk_add_f32 v[114:115], v[74:75], v[106:107]
	s_waitcnt vmcnt(6)
	v_pk_add_f32 v[110:111], v[70:71], v[102:103]
	s_waitcnt vmcnt(5)
	v_pk_add_f32 v[78:79], v[66:67], v[98:99]
	v_readlane_b32 s53, v254, 9
	v_readlane_b32 s54, v254, 10
	v_readlane_b32 s55, v254, 11
	v_readlane_b32 s56, v254, 12
	v_readlane_b32 s57, v254, 13
	global_store_dwordx4 v[138:139], v[118:121], off
	s_cbranch_vccnz .LBB0_2157
	v_lshlrev_b64 v[66:67], 12, v[140:141]
	v_lshl_add_u64 v[66:67], v[66:67], 0, v[182:183]
	v_readlane_b32 s2, v254, 40
	v_lshlrev_b64 v[74:75], 1, v[66:67]
	v_readlane_b32 s3, v254, 41
	s_nop 0
	v_cvt_pk_bf16_f32 v70, v118, v119
	s_nop 0
	v_cvt_pk_bf16_f32 v71, v120, v121
	v_pk_add_f32 v[116:117], v[76:77], v[108:109]
	v_pk_add_f32 v[112:113], v[72:73], v[104:105]
	v_lshl_add_u64 v[66:67], s[2:3], 0, v[74:75]
	global_store_dwordx2 v[66:67], v[70:71], off
	v_mul_f32_e32 v66, v119, v119
	v_mul_f32_e32 v67, v121, v121
	v_fmac_f32_e32 v66, v118, v118
	v_fmac_f32_e32 v67, v120, v120
	v_or_b32_e32 v70, 32, v74
	v_mov_b32_e32 v71, v75
	v_add_f32_e32 v80, v66, v67
	global_store_dwordx4 v[138:139], v[114:117], off offset:1024
	s_nop 0
	v_cvt_pk_bf16_f32 v66, v114, v115
	s_nop 0
	v_cvt_pk_bf16_f32 v67, v116, v117
	v_lshl_add_u64 v[70:71], s[2:3], 0, v[70:71]
	global_store_dwordx2 v[70:71], v[66:67], off
	v_mul_f32_e32 v66, v115, v115
	v_mul_f32_e32 v67, v117, v117
	v_fmac_f32_e32 v66, v114, v114
	v_fmac_f32_e32 v67, v116, v116
	v_add_f32_e32 v66, v66, v67
	v_add_f32_e32 v66, v80, v66
	v_mul_f32_e32 v67, v111, v111
	v_mul_f32_e32 v80, v113, v113
	v_fmac_f32_e32 v67, v110, v110
	v_fmac_f32_e32 v80, v112, v112
	v_add_f32_e32 v67, v67, v80
	v_pk_add_f32 v[80:81], v[68:69], v[100:101]
	v_add_f32_e32 v66, v66, v67
	v_mul_f32_e32 v67, v79, v79
	v_mul_f32_e32 v102, v81, v81
	v_fmac_f32_e32 v67, v78, v78
	v_fmac_f32_e32 v102, v80, v80
	v_add_f32_e32 v67, v67, v102
	v_and_b32_e32 v102, 64, v195
	v_add_f32_e32 v67, v66, v67
	v_xor_b32_e32 v66, 16, v195
	v_add_u32_e32 v102, 64, v102
	v_cmp_lt_i32_e32 vcc, v66, v102
	v_or_b32_e32 v98, 0x100, v74
	v_mov_b32_e32 v99, v75
	v_cndmask_b32_e32 v66, v195, v66, vcc
	v_lshlrev_b32_e32 v66, 2, v66
	ds_bpermute_b32 v103, v66, v67
	global_store_dwordx4 v[138:139], v[110:113], off offset:2048
	s_nop 0
	v_cvt_pk_bf16_f32 v70, v110, v111
	s_nop 0
	v_cvt_pk_bf16_f32 v71, v112, v113
	v_lshl_add_u64 v[98:99], s[2:3], 0, v[98:99]
	global_store_dwordx2 v[98:99], v[70:71], off
	global_store_dwordx4 v[138:139], v[78:81], off offset:3072
	s_waitcnt lgkmcnt(0)
	v_add_f32_e32 v70, v67, v103
	v_xor_b32_e32 v67, 32, v195
	v_cmp_lt_i32_e32 vcc, v67, v102
	v_or_b32_e32 v74, 0x120, v74
	v_lshl_add_u64 v[74:75], s[2:3], 0, v[74:75]
	v_cndmask_b32_e32 v67, v195, v67, vcc
	v_lshlrev_b32_e32 v67, 2, v67
	ds_bpermute_b32 v71, v67, v70
	s_nop 0
	v_cvt_pk_bf16_f32 v98, v78, v79
	s_nop 0
	v_cvt_pk_bf16_f32 v99, v80, v81
	global_store_dwordx2 v[74:75], v[98:99], off
	s_and_saveexec_b64 s[2:3], s[6:7]
	s_cbranch_execz .LBB0_2119
	v_lshl_add_u64 v[74:75], v[140:141], 2, s[10:11]
	s_waitcnt lgkmcnt(0)
	v_add_f32_e32 v70, v70, v71
	global_atomic_add_f32 v[74:75], v70, off

;     __device__ __forceinline__ void load_row(RowIn& R, size_t off) const {
; #pragma unroll
;         for (int bj = 0; bj < 2; ++bj)
; #pragma unroll
;             for (int n = 0; n < 2; ++n) { const size_t o = off + bj * HALF + n * 16; R.b[bj][n] = *(const f32x4*)(res + o); if (MODE == 1) R.pw[bj][n] = *(const u32x2*)(PP + o); }
;     }
;     __device__ __forceinline__ void operator()(const typename AccT<I8>::type (&acc)[2][2][4][2], const Unit& u, int wr, int wc, int fr, int fq) const {
;         const int row0 = u.pm * BM + wr * 64 + fr, col0 = u.pn * BM + wc * 32 + 4 * fq;
;         f32x4 sv[2][2];
;         if (I8) {
; #pragma unroll
;             for (int bj = 0; bj < 2; ++bj)
; #pragma unroll
;                 for (int n = 0; n < 2; ++n) sv[bj][n] = *(const f32x4*)(swc + col0 + bj * HALF + n * 16);
;         }
;         float rsv[8];
; #pragma unroll
;         for (int s = 0; s < 8; ++s) { const int r = row0 + (s >> 2) * HALF + (s & 3) * 16; float rs = 1.f; if (MODE == 1) rs = __builtin_amdgcn_rsqf(rstd[r] * (1.0f / 4096.0f) + 1e-6f); if (I8) rs *= sxr[r]; rsv[s] = rs; }
;         RowIn cur, nxt;
;         load_row(cur, (size_t)row0 * 4096 + col0);
; #pragma unroll
;         for (int s = 0; s < 8; ++s) { const int ai = s >> 2, m = s & 3; const int r = row0 + ai * HALF + m * 16; const size_t off = (size_t)r * 4096 + col0;
;                 if (s + 1 < 8) load_row(nxt, (size_t)(row0 + ((s + 1) >> 2) * HALF + ((s + 1) & 3) * 16) * 4096 + col0);
;                 const float rs = rsv[s];
;                 float ss = 0.f, mx = 0.f;
; #pragma unroll
;                 for (int bj = 0; bj < 2; ++bj)
; #pragma unroll
;                     for (int n = 0; n < 2; ++n) { const size_t o = off + bj * HALF + n * 16; const f32x4 b = cur.b[bj][n]; f32x4 v;
;                         if constexpr (I8) v = __builtin_convertvector(acc[ai][bj][m][n], f32x4) * rs * sv[bj][n]; else v = acc[ai][bj][m][n];
;                         if (MODE == 1) { const u32x2 pw = cur.pw[bj][n]; const f32x4 pp = (f32x4){bf_lo(pw.x), bf_hi(pw.x), bf_lo(pw.y), bf_hi(pw.y)}; v = sig4(I8 ? v : v * rs) * pp; }
;                         const f32x4 x = b + v; *(f32x4*)(out + o) = x;
;                         if (MODE == 0 && XB) { u32x2 w; w.x = cvt_pk_bf16(x[0], x[1]); w.y = cvt_pk_bf16(x[2], x[3]); *(u32x2*)(XB + o) = w; ss += (x[0] * x[0] + x[1] * x[1]) + (x[2] * x[2] + x[3] * x[3]);
.LBB0_2122:
	v_pk_add_f32 v[116:117], v[76:77], v[108:109]
	v_pk_add_f32 v[112:113], v[72:73], v[104:105]
	v_pk_add_f32 v[80:81], v[68:69], v[100:101]
	global_store_dwordx4 v[138:139], v[114:117], off offset:1024
	global_store_dwordx4 v[138:139], v[110:113], off offset:2048
	global_store_dwordx4 v[138:139], v[78:81], off offset:3072
.LBB0_2123:
	v_or_b32_e32 v108, 16, v122
	v_ashrrev_i32_e32 v109, 31, v108
	v_readlane_b32 s52, v254, 8
	s_waitcnt lgkmcnt(0)
	v_lshlrev_b64 v[66:67], 14, v[108:109]
	v_readlane_b32 s58, v254, 14
	v_readlane_b32 s59, v254, 15
	s_waitcnt vmcnt(4)
	v_pk_add_f32 v[104:105], v[64:65], v[96:97]
	v_pk_add_f32 v[102:103], v[62:63], v[94:95]
	v_lshl_add_u64 v[66:67], s[58:59], 0, v[66:67]
	s_mov_b64 s[98:99], 0x5000
	v_lshl_add_u64 v[106:107], v[250:251], 0, s[98:99]
	s_mov_b64 s[98:99], 0x5000
	v_lshl_add_u64 v[252:253], v[250:251], 0, s[98:99]
	global_load_dwordx4 v[78:81], v[252:253], off
	global_load_dwordx4 v[74:77], v[252:253], off offset:1024
	global_load_dwordx4 v[70:73], v[252:253], off offset:2048
	global_load_dwordx4 v[66:69], v[252:253], off offset:3072
	s_and_b64 vcc, exec, s[8:9]
	s_waitcnt vmcnt(7)
	v_pk_add_f32 v[98:99], v[58:59], v[90:91]
	s_waitcnt vmcnt(6)
	v_pk_add_f32 v[94:95], v[54:55], v[86:87]
	s_waitcnt vmcnt(5)
	v_pk_add_f32 v[62:63], v[50:51], v[82:83]
	v_readlane_b32 s53, v254, 9
	v_readlane_b32 s54, v254, 10
	v_readlane_b32 s55, v254, 11
	v_readlane_b32 s56, v254, 12
	v_readlane_b32 s57, v254, 13
	global_store_dwordx4 v[124:125], v[102:105], off
	s_cbranch_vccnz .LBB0_2158
	v_lshlrev_b64 v[50:51], 12, v[122:123]
	v_lshl_add_u64 v[50:51], v[50:51], 0, v[182:183]
	v_readlane_b32 s2, v254, 40
	v_lshlrev_b64 v[58:59], 1, v[50:51]
	v_readlane_b32 s3, v254, 41
	s_nop 0
	v_cvt_pk_bf16_f32 v54, v102, v103
	s_nop 0
	v_cvt_pk_bf16_f32 v55, v104, v105
	v_pk_add_f32 v[100:101], v[60:61], v[92:93]
	v_pk_add_f32 v[96:97], v[56:57], v[88:89]
	v_lshl_add_u64 v[50:51], s[2:3], 0, v[58:59]
	global_store_dwordx2 v[50:51], v[54:55], off
	v_mul_f32_e32 v50, v103, v103
	v_mul_f32_e32 v51, v105, v105
	v_fmac_f32_e32 v50, v102, v102
	v_fmac_f32_e32 v51, v104, v104
	v_or_b32_e32 v54, 32, v58
	v_mov_b32_e32 v55, v59
	v_add_f32_e32 v64, v50, v51
	global_store_dwordx4 v[124:125], v[98:101], off offset:1024
	s_nop 0
	v_cvt_pk_bf16_f32 v50, v98, v99
	s_nop 0
	v_cvt_pk_bf16_f32 v51, v100, v101
	v_lshl_add_u64 v[54:55], s[2:3], 0, v[54:55]
	global_store_dwordx2 v[54:55], v[50:51], off
	v_mul_f32_e32 v50, v99, v99
	v_mul_f32_e32 v51, v101, v101
	v_fmac_f32_e32 v50, v98, v98
	v_fmac_f32_e32 v51, v100, v100
	v_add_f32_e32 v50, v50, v51
	v_add_f32_e32 v50, v64, v50
	v_mul_f32_e32 v51, v95, v95
	v_mul_f32_e32 v64, v97, v97
	v_fmac_f32_e32 v51, v94, v94
	v_fmac_f32_e32 v64, v96, v96
	v_add_f32_e32 v51, v51, v64
	v_pk_add_f32 v[64:65], v[52:53], v[84:85]
	v_add_f32_e32 v50, v50, v51
	v_mul_f32_e32 v51, v63, v63
	v_mul_f32_e32 v86, v65, v65
	v_fmac_f32_e32 v51, v62, v62
	v_fmac_f32_e32 v86, v64, v64
	v_add_f32_e32 v51, v51, v86
	v_and_b32_e32 v86, 64, v195
	v_add_f32_e32 v51, v50, v51
	v_xor_b32_e32 v50, 16, v195
	v_add_u32_e32 v86, 64, v86
	v_cmp_lt_i32_e32 vcc, v50, v86
	v_or_b32_e32 v82, 0x100, v58
	v_mov_b32_e32 v83, v59
	v_cndmask_b32_e32 v50, v195, v50, vcc
	v_lshlrev_b32_e32 v50, 2, v50
	ds_bpermute_b32 v87, v50, v51
	global_store_dwordx4 v[124:125], v[94:97], off offset:2048
	s_nop 0
	v_cvt_pk_bf16_f32 v54, v94, v95
	s_nop 0
	v_cvt_pk_bf16_f32 v55, v96, v97
	v_lshl_add_u64 v[82:83], s[2:3], 0, v[82:83]
	global_store_dwordx2 v[82:83], v[54:55], off
	global_store_dwordx4 v[124:125], v[62:65], off offset:3072
	s_waitcnt lgkmcnt(0)
	v_add_f32_e32 v54, v51, v87
	v_xor_b32_e32 v51, 32, v195
	v_cmp_lt_i32_e32 vcc, v51, v86
	v_or_b32_e32 v58, 0x120, v58
	v_lshl_add_u64 v[58:59], s[2:3], 0, v[58:59]
	v_cndmask_b32_e32 v51, v195, v51, vcc
	v_lshlrev_b32_e32 v51, 2, v51
	ds_bpermute_b32 v55, v51, v54
	s_nop 0
	v_cvt_pk_bf16_f32 v82, v62, v63
	s_nop 0
	v_cvt_pk_bf16_f32 v83, v64, v65
	global_store_dwordx2 v[58:59], v[82:83], off
	s_and_saveexec_b64 s[2:3], s[6:7]
	s_cbranch_execz .LBB0_2126
	v_lshl_add_u64 v[58:59], v[122:123], 2, s[10:11]
	s_waitcnt lgkmcnt(0)
	v_add_f32_e32 v54, v54, v55
	global_atomic_add_f32 v[58:59], v54, off

;     __device__ __forceinline__ void load_row(RowIn& R, size_t off) const {
; #pragma unroll
;         for (int bj = 0; bj < 2; ++bj)
; #pragma unroll
;             for (int n = 0; n < 2; ++n) { const size_t o = off + bj * HALF + n * 16; R.b[bj][n] = *(const f32x4*)(res + o); if (MODE == 1) R.pw[bj][n] = *(const u32x2*)(PP + o); }
;     }
;     __device__ __forceinline__ void operator()(const typename AccT<I8>::type (&acc)[2][2][4][2], const Unit& u, int wr, int wc, int fr, int fq) const {
;         const int row0 = u.pm * BM + wr * 64 + fr, col0 = u.pn * BM + wc * 32 + 4 * fq;
;         f32x4 sv[2][2];
;         if (I8) {
; #pragma unroll
;             for (int bj = 0; bj < 2; ++bj)
; #pragma unroll
;                 for (int n = 0; n < 2; ++n) sv[bj][n] = *(const f32x4*)(swc + col0 + bj * HALF + n * 16);
;         }
;         float rsv[8];
; #pragma unroll
;         for (int s = 0; s < 8; ++s) { const int r = row0 + (s >> 2) * HALF + (s & 3) * 16; float rs = 1.f; if (MODE == 1) rs = __builtin_amdgcn_rsqf(rstd[r] * (1.0f / 4096.0f) + 1e-6f); if (I8) rs *= sxr[r]; rsv[s] = rs; }
;         RowIn cur, nxt;
;         load_row(cur, (size_t)row0 * 4096 + col0);
; #pragma unroll
;         for (int s = 0; s < 8; ++s) { const int ai = s >> 2, m = s & 3; const int r = row0 + ai * HALF + m * 16; const size_t off = (size_t)r * 4096 + col0;
;                 if (s + 1 < 8) load_row(nxt, (size_t)(row0 + ((s + 1) >> 2) * HALF + ((s + 1) & 3) * 16) * 4096 + col0);
;                 const float rs = rsv[s];
;                 float ss = 0.f, mx = 0.f;
; #pragma unroll
;                 for (int bj = 0; bj < 2; ++bj)
; #pragma unroll
;                     for (int n = 0; n < 2; ++n) { const size_t o = off + bj * HALF + n * 16; const f32x4 b = cur.b[bj][n]; f32x4 v;
;                         if constexpr (I8) v = __builtin_convertvector(acc[ai][bj][m][n], f32x4) * rs * sv[bj][n]; else v = acc[ai][bj][m][n];
;                         if (MODE == 1) { const u32x2 pw = cur.pw[bj][n]; const f32x4 pp = (f32x4){bf_lo(pw.x), bf_hi(pw.x), bf_lo(pw.y), bf_hi(pw.y)}; v = sig4(I8 ? v : v * rs) * pp; }
;                         const f32x4 x = b + v; *(f32x4*)(out + o) = x;
;                         if (MODE == 0 && XB) { u32x2 w; w.x = cvt_pk_bf16(x[0], x[1]); w.y = cvt_pk_bf16(x[2], x[3]); *(u32x2*)(XB + o) = w; ss += (x[0] * x[0] + x[1] * x[1]) + (x[2] * x[2] + x[3] * x[3]);
.LBB0_2129:
	v_pk_add_f32 v[100:101], v[60:61], v[92:93]
	v_pk_add_f32 v[96:97], v[56:57], v[88:89]
	v_pk_add_f32 v[64:65], v[52:53], v[84:85]
	global_store_dwordx4 v[124:125], v[98:101], off offset:1024
	global_store_dwordx4 v[124:125], v[94:97], off offset:2048
	global_store_dwordx4 v[124:125], v[62:65], off offset:3072
.LBB0_2130:
	v_or_b32_e32 v92, 32, v122
	v_ashrrev_i32_e32 v93, 31, v92
	v_readlane_b32 s52, v254, 8
	s_waitcnt lgkmcnt(0)
	v_lshlrev_b64 v[50:51], 14, v[92:93]
	v_readlane_b32 s58, v254, 14
	v_readlane_b32 s59, v254, 15
	s_waitcnt vmcnt(4)
	v_pk_add_f32 v[88:89], v[48:49], v[80:81]
	v_pk_add_f32 v[86:87], v[46:47], v[78:79]
	v_lshl_add_u64 v[50:51], s[58:59], 0, v[50:51]
	s_mov_b64 s[98:99], 0x6000
	v_lshl_add_u64 v[90:91], v[250:251], 0, s[98:99]
	s_mov_b64 s[98:99], 0x6000
	v_lshl_add_u64 v[252:253], v[250:251], 0, s[98:99]
	global_load_dwordx4 v[62:65], v[252:253], off
	global_load_dwordx4 v[58:61], v[252:253], off offset:1024
	global_load_dwordx4 v[54:57], v[252:253], off offset:2048
	global_load_dwordx4 v[50:53], v[252:253], off offset:3072
	s_and_b64 vcc, exec, s[8:9]
	s_waitcnt vmcnt(7)
	v_pk_add_f32 v[82:83], v[42:43], v[74:75]
	s_waitcnt vmcnt(6)
	v_pk_add_f32 v[78:79], v[38:39], v[70:71]
	s_waitcnt vmcnt(5)
	v_pk_add_f32 v[46:47], v[34:35], v[66:67]
	v_readlane_b32 s53, v254, 9
	v_readlane_b32 s54, v254, 10
	v_readlane_b32 s55, v254, 11
	v_readlane_b32 s56, v254, 12
	v_readlane_b32 s57, v254, 13
	global_store_dwordx4 v[106:107], v[86:89], off
	s_cbranch_vccnz .LBB0_2159
	v_lshlrev_b64 v[34:35], 12, v[108:109]
	v_lshl_add_u64 v[34:35], v[34:35], 0, v[182:183]
	v_readlane_b32 s2, v254, 40
	v_lshlrev_b64 v[42:43], 1, v[34:35]
	v_readlane_b32 s3, v254, 41
	s_nop 0
	v_cvt_pk_bf16_f32 v38, v86, v87
	s_nop 0
	v_cvt_pk_bf16_f32 v39, v88, v89
	v_pk_add_f32 v[84:85], v[44:45], v[76:77]
	v_pk_add_f32 v[80:81], v[40:41], v[72:73]
	v_lshl_add_u64 v[34:35], s[2:3], 0, v[42:43]
	global_store_dwordx2 v[34:35], v[38:39], off
	v_mul_f32_e32 v34, v87, v87
	v_mul_f32_e32 v35, v89, v89
	v_fmac_f32_e32 v34, v86, v86
	v_fmac_f32_e32 v35, v88, v88
	v_or_b32_e32 v38, 32, v42
	v_mov_b32_e32 v39, v43
	v_add_f32_e32 v48, v34, v35
	global_store_dwordx4 v[106:107], v[82:85], off offset:1024
	s_nop 0
	v_cvt_pk_bf16_f32 v34, v82, v83
	s_nop 0
	v_cvt_pk_bf16_f32 v35, v84, v85
	v_lshl_add_u64 v[38:39], s[2:3], 0, v[38:39]
	global_store_dwordx2 v[38:39], v[34:35], off
	v_mul_f32_e32 v34, v83, v83
	v_mul_f32_e32 v35, v85, v85
	v_fmac_f32_e32 v34, v82, v82
	v_fmac_f32_e32 v35, v84, v84
	v_add_f32_e32 v34, v34, v35
	v_add_f32_e32 v34, v48, v34
	v_mul_f32_e32 v35, v79, v79
	v_mul_f32_e32 v48, v81, v81
	v_fmac_f32_e32 v35, v78, v78
	v_fmac_f32_e32 v48, v80, v80
	v_add_f32_e32 v35, v35, v48
	v_pk_add_f32 v[48:49], v[36:37], v[68:69]
	v_add_f32_e32 v34, v34, v35
	v_mul_f32_e32 v35, v47, v47
	v_mul_f32_e32 v70, v49, v49
	v_fmac_f32_e32 v35, v46, v46
	v_fmac_f32_e32 v70, v48, v48
	v_add_f32_e32 v35, v35, v70
	v_and_b32_e32 v70, 64, v195
	v_add_f32_e32 v35, v34, v35
	v_xor_b32_e32 v34, 16, v195
	v_add_u32_e32 v70, 64, v70
	v_cmp_lt_i32_e32 vcc, v34, v70
	v_or_b32_e32 v66, 0x100, v42
	v_mov_b32_e32 v67, v43
	v_cndmask_b32_e32 v34, v195, v34, vcc
	v_lshlrev_b32_e32 v34, 2, v34
	ds_bpermute_b32 v71, v34, v35
	global_store_dwordx4 v[106:107], v[78:81], off offset:2048
	s_nop 0
	v_cvt_pk_bf16_f32 v38, v78, v79
	s_nop 0
	v_cvt_pk_bf16_f32 v39, v80, v81
	v_lshl_add_u64 v[66:67], s[2:3], 0, v[66:67]
	global_store_dwordx2 v[66:67], v[38:39], off
	global_store_dwordx4 v[106:107], v[46:49], off offset:3072
	s_waitcnt lgkmcnt(0)
	v_add_f32_e32 v38, v35, v71
	v_xor_b32_e32 v35, 32, v195
	v_cmp_lt_i32_e32 vcc, v35, v70
	v_or_b32_e32 v42, 0x120, v42
	v_lshl_add_u64 v[42:43], s[2:3], 0, v[42:43]
	v_cndmask_b32_e32 v35, v195, v35, vcc
	v_lshlrev_b32_e32 v35, 2, v35
	ds_bpermute_b32 v39, v35, v38
	s_nop 0
	v_cvt_pk_bf16_f32 v66, v46, v47
	s_nop 0
	v_cvt_pk_bf16_f32 v67, v48, v49
	global_store_dwordx2 v[42:43], v[66:67], off
	s_and_saveexec_b64 s[2:3], s[6:7]
	s_cbranch_execz .LBB0_2133
	v_lshl_add_u64 v[42:43], v[108:109], 2, s[10:11]
	s_waitcnt lgkmcnt(0)
	v_add_f32_e32 v38, v38, v39
	global_atomic_add_f32 v[42:43], v38, off

;     __device__ __forceinline__ void load_row(RowIn& R, size_t off) const {
; #pragma unroll
;         for (int bj = 0; bj < 2; ++bj)
; #pragma unroll
;             for (int n = 0; n < 2; ++n) { const size_t o = off + bj * HALF + n * 16; R.b[bj][n] = *(const f32x4*)(res + o); if (MODE == 1) R.pw[bj][n] = *(const u32x2*)(PP + o); }
;     }
;     __device__ __forceinline__ void operator()(const typename AccT<I8>::type (&acc)[2][2][4][2], const Unit& u, int wr, int wc, int fr, int fq) const {
;         const int row0 = u.pm * BM + wr * 64 + fr, col0 = u.pn * BM + wc * 32 + 4 * fq;
;         f32x4 sv[2][2];
;         if (I8) {
; #pragma unroll
;             for (int bj = 0; bj < 2; ++bj)
; #pragma unroll
;                 for (int n = 0; n < 2; ++n) sv[bj][n] = *(const f32x4*)(swc + col0 + bj * HALF + n * 16);
;         }
;         float rsv[8];
; #pragma unroll
;         for (int s = 0; s < 8; ++s) { const int r = row0 + (s >> 2) * HALF + (s & 3) * 16; float rs = 1.f; if (MODE == 1) rs = __builtin_amdgcn_rsqf(rstd[r] * (1.0f / 4096.0f) + 1e-6f); if (I8) rs *= sxr[r]; rsv[s] = rs; }
;         RowIn cur, nxt;
;         load_row(cur, (size_t)row0 * 4096 + col0);
; #pragma unroll
;         for (int s = 0; s < 8; ++s) { const int ai = s >> 2, m = s & 3; const int r = row0 + ai * HALF + m * 16; const size_t off = (size_t)r * 4096 + col0;
;                 if (s + 1 < 8) load_row(nxt, (size_t)(row0 + ((s + 1) >> 2) * HALF + ((s + 1) & 3) * 16) * 4096 + col0);
;                 const float rs = rsv[s];
;                 float ss = 0.f, mx = 0.f;
; #pragma unroll
;                 for (int bj = 0; bj < 2; ++bj)
; #pragma unroll
;                     for (int n = 0; n < 2; ++n) { const size_t o = off + bj * HALF + n * 16; const f32x4 b = cur.b[bj][n]; f32x4 v;
;                         if constexpr (I8) v = __builtin_convertvector(acc[ai][bj][m][n], f32x4) * rs * sv[bj][n]; else v = acc[ai][bj][m][n];
;                         if (MODE == 1) { const u32x2 pw = cur.pw[bj][n]; const f32x4 pp = (f32x4){bf_lo(pw.x), bf_hi(pw.x), bf_lo(pw.y), bf_hi(pw.y)}; v = sig4(I8 ? v : v * rs) * pp; }
;                         const f32x4 x = b + v; *(f32x4*)(out + o) = x;
;                         if (MODE == 0 && XB) { u32x2 w; w.x = cvt_pk_bf16(x[0], x[1]); w.y = cvt_pk_bf16(x[2], x[3]); *(u32x2*)(XB + o) = w; ss += (x[0] * x[0] + x[1] * x[1]) + (x[2] * x[2] + x[3] * x[3]);
.LBB0_2136:
	v_pk_add_f32 v[84:85], v[44:45], v[76:77]
	v_pk_add_f32 v[80:81], v[40:41], v[72:73]
	v_pk_add_f32 v[48:49], v[36:37], v[68:69]
	global_store_dwordx4 v[106:107], v[82:85], off offset:1024
	global_store_dwordx4 v[106:107], v[78:81], off offset:2048
	global_store_dwordx4 v[106:107], v[46:49], off offset:3072
.LBB0_2137:
	v_or_b32_e32 v76, 48, v122
	v_ashrrev_i32_e32 v77, 31, v76
	v_readlane_b32 s52, v254, 8
	s_waitcnt lgkmcnt(0)
	v_lshlrev_b64 v[34:35], 14, v[76:77]
	v_readlane_b32 s58, v254, 14
	v_readlane_b32 s59, v254, 15
	s_waitcnt vmcnt(4)
	v_pk_add_f32 v[72:73], v[32:33], v[64:65]
	v_pk_add_f32 v[70:71], v[30:31], v[62:63]
	v_lshl_add_u64 v[34:35], s[58:59], 0, v[34:35]
	s_mov_b64 s[98:99], 0x7000
	v_lshl_add_u64 v[74:75], v[250:251], 0, s[98:99]
	s_mov_b64 s[98:99], 0x7000
	v_lshl_add_u64 v[252:253], v[250:251], 0, s[98:99]
	global_load_dwordx4 v[46:49], v[252:253], off
	global_load_dwordx4 v[42:45], v[252:253], off offset:1024
	global_load_dwordx4 v[38:41], v[252:253], off offset:2048
	global_load_dwordx4 v[34:37], v[252:253], off offset:3072
	s_and_b64 vcc, exec, s[8:9]
	s_waitcnt vmcnt(7)
	v_pk_add_f32 v[66:67], v[26:27], v[58:59]
	s_waitcnt vmcnt(6)
	v_pk_add_f32 v[62:63], v[18:19], v[54:55]
	s_waitcnt vmcnt(5)
	v_pk_add_f32 v[30:31], v[14:15], v[50:51]
	v_readlane_b32 s53, v254, 9
	v_readlane_b32 s54, v254, 10
	v_readlane_b32 s55, v254, 11
	v_readlane_b32 s56, v254, 12
	v_readlane_b32 s57, v254, 13
	global_store_dwordx4 v[90:91], v[70:73], off
	s_cbranch_vccnz .LBB0_2160
	v_lshlrev_b64 v[14:15], 12, v[92:93]
	v_lshl_add_u64 v[14:15], v[14:15], 0, v[182:183]
	v_readlane_b32 s2, v254, 40
	v_lshlrev_b64 v[26:27], 1, v[14:15]
	v_readlane_b32 s3, v254, 41
	s_nop 0
	v_cvt_pk_bf16_f32 v18, v70, v71
	s_nop 0
	v_cvt_pk_bf16_f32 v19, v72, v73
	v_pk_add_f32 v[68:69], v[28:29], v[60:61]
	v_pk_add_f32 v[64:65], v[20:21], v[56:57]
	v_lshl_add_u64 v[14:15], s[2:3], 0, v[26:27]
	global_store_dwordx2 v[14:15], v[18:19], off
	v_mul_f32_e32 v14, v71, v71
	v_mul_f32_e32 v15, v73, v73
	v_fmac_f32_e32 v14, v70, v70
	v_fmac_f32_e32 v15, v72, v72
	v_or_b32_e32 v18, 32, v26
	v_mov_b32_e32 v19, v27
	v_add_f32_e32 v32, v14, v15
	global_store_dwordx4 v[90:91], v[66:69], off offset:1024
	s_nop 0
	v_cvt_pk_bf16_f32 v14, v66, v67
	s_nop 0
	v_cvt_pk_bf16_f32 v15, v68, v69
	v_lshl_add_u64 v[18:19], s[2:3], 0, v[18:19]
	global_store_dwordx2 v[18:19], v[14:15], off
	v_mul_f32_e32 v14, v67, v67
	v_mul_f32_e32 v15, v69, v69
	v_fmac_f32_e32 v14, v66, v66
	v_fmac_f32_e32 v15, v68, v68
	v_add_f32_e32 v14, v14, v15
	v_add_f32_e32 v14, v32, v14
	v_mul_f32_e32 v15, v63, v63
	v_mul_f32_e32 v32, v65, v65
	v_fmac_f32_e32 v15, v62, v62
	v_fmac_f32_e32 v32, v64, v64
	v_add_f32_e32 v15, v15, v32
	v_pk_add_f32 v[32:33], v[16:17], v[52:53]
	v_add_f32_e32 v14, v14, v15
	v_mul_f32_e32 v15, v31, v31
	v_mul_f32_e32 v54, v33, v33
	v_fmac_f32_e32 v15, v30, v30
	v_fmac_f32_e32 v54, v32, v32
	v_add_f32_e32 v15, v15, v54
	v_and_b32_e32 v54, 64, v195
	v_add_f32_e32 v15, v14, v15
	v_xor_b32_e32 v14, 16, v195
	v_add_u32_e32 v54, 64, v54
	v_cmp_lt_i32_e32 vcc, v14, v54
	v_or_b32_e32 v50, 0x100, v26
	v_mov_b32_e32 v51, v27
	v_cndmask_b32_e32 v14, v195, v14, vcc
	v_lshlrev_b32_e32 v14, 2, v14
	ds_bpermute_b32 v55, v14, v15
	global_store_dwordx4 v[90:91], v[62:65], off offset:2048
	s_nop 0
	v_cvt_pk_bf16_f32 v18, v62, v63
	s_nop 0
	v_cvt_pk_bf16_f32 v19, v64, v65
	v_lshl_add_u64 v[50:51], s[2:3], 0, v[50:51]
	global_store_dwordx2 v[50:51], v[18:19], off
	global_store_dwordx4 v[90:91], v[30:33], off offset:3072
	s_waitcnt lgkmcnt(0)
	v_add_f32_e32 v18, v15, v55
	v_xor_b32_e32 v15, 32, v195
	v_cmp_lt_i32_e32 vcc, v15, v54
	v_or_b32_e32 v26, 0x120, v26
	v_lshl_add_u64 v[26:27], s[2:3], 0, v[26:27]
	v_cndmask_b32_e32 v15, v195, v15, vcc
	v_lshlrev_b32_e32 v15, 2, v15
	ds_bpermute_b32 v19, v15, v18
	s_nop 0
	v_cvt_pk_bf16_f32 v50, v30, v31
	s_nop 0
	v_cvt_pk_bf16_f32 v51, v32, v33
	global_store_dwordx2 v[26:27], v[50:51], off
	s_and_saveexec_b64 s[2:3], s[6:7]
	s_cbranch_execz .LBB0_2140
	v_lshl_add_u64 v[26:27], v[92:93], 2, s[10:11]
	s_waitcnt lgkmcnt(0)
	v_add_f32_e32 v18, v18, v19
	global_atomic_add_f32 v[26:27], v18, off

;     __device__ __forceinline__ void load_row(RowIn& R, size_t off) const {
; #pragma unroll
;         for (int bj = 0; bj < 2; ++bj)
; #pragma unroll
;             for (int n = 0; n < 2; ++n) { const size_t o = off + bj * HALF + n * 16; R.b[bj][n] = *(const f32x4*)(res + o); if (MODE == 1) R.pw[bj][n] = *(const u32x2*)(PP + o); }
;     }
;     __device__ __forceinline__ void operator()(const typename AccT<I8>::type (&acc)[2][2][4][2], const Unit& u, int wr, int wc, int fr, int fq) const {
;         const int row0 = u.pm * BM + wr * 64 + fr, col0 = u.pn * BM + wc * 32 + 4 * fq;
;         f32x4 sv[2][2];
;         if (I8) {
; #pragma unroll
;             for (int bj = 0; bj < 2; ++bj)
; #pragma unroll
;                 for (int n = 0; n < 2; ++n) sv[bj][n] = *(const f32x4*)(swc + col0 + bj * HALF + n * 16);
;         }
;         float rsv[8];
; #pragma unroll
;         for (int s = 0; s < 8; ++s) { const int r = row0 + (s >> 2) * HALF + (s & 3) * 16; float rs = 1.f; if (MODE == 1) rs = __builtin_amdgcn_rsqf(rstd[r] * (1.0f / 4096.0f) + 1e-6f); if (I8) rs *= sxr[r]; rsv[s] = rs; }
;         RowIn cur, nxt;
;         load_row(cur, (size_t)row0 * 4096 + col0);
; #pragma unroll
;         for (int s = 0; s < 8; ++s) { const int ai = s >> 2, m = s & 3; const int r = row0 + ai * HALF + m * 16; const size_t off = (size_t)r * 4096 + col0;
;                 if (s + 1 < 8) load_row(nxt, (size_t)(row0 + ((s + 1) >> 2) * HALF + ((s + 1) & 3) * 16) * 4096 + col0);
;                 const float rs = rsv[s];
;                 float ss = 0.f, mx = 0.f;
; #pragma unroll
;                 for (int bj = 0; bj < 2; ++bj)
; #pragma unroll
;                     for (int n = 0; n < 2; ++n) { const size_t o = off + bj * HALF + n * 16; const f32x4 b = cur.b[bj][n]; f32x4 v;
;                         if constexpr (I8) v = __builtin_convertvector(acc[ai][bj][m][n], f32x4) * rs * sv[bj][n]; else v = acc[ai][bj][m][n];
;                         if (MODE == 1) { const u32x2 pw = cur.pw[bj][n]; const f32x4 pp = (f32x4){bf_lo(pw.x), bf_hi(pw.x), bf_lo(pw.y), bf_hi(pw.y)}; v = sig4(I8 ? v : v * rs) * pp; }
;                         const f32x4 x = b + v; *(f32x4*)(out + o) = x;
;                         if (MODE == 0 && XB) { u32x2 w; w.x = cvt_pk_bf16(x[0], x[1]); w.y = cvt_pk_bf16(x[2], x[3]); *(u32x2*)(XB + o) = w; ss += (x[0] * x[0] + x[1] * x[1]) + (x[2] * x[2] + x[3] * x[3]);
.LBB0_2143:
	v_pk_add_f32 v[68:69], v[28:29], v[60:61]
	v_pk_add_f32 v[64:65], v[20:21], v[56:57]
	v_pk_add_f32 v[32:33], v[16:17], v[52:53]
	global_store_dwordx4 v[90:91], v[66:69], off offset:1024
	global_store_dwordx4 v[90:91], v[62:65], off offset:2048
	global_store_dwordx4 v[90:91], v[30:33], off offset:3072
.LBB0_2144:
	s_waitcnt vmcnt(4)
	v_pk_add_f32 v[28:29], v[24:25], v[48:49]
	v_pk_add_f32 v[26:27], v[22:23], v[46:47]
	s_and_b64 vcc, exec, s[8:9]
	s_waitcnt vmcnt(3)
	v_pk_add_f32 v[22:23], v[10:11], v[42:43]
	s_waitcnt vmcnt(2)
	v_pk_add_f32 v[18:19], v[6:7], v[38:39]
	s_waitcnt vmcnt(1) lgkmcnt(0)
	v_pk_add_f32 v[14:15], v[2:3], v[34:35]
	global_store_dwordx4 v[74:75], v[26:29], off
	s_cbranch_vccnz .LBB0_2161
	v_lshlrev_b64 v[2:3], 12, v[76:77]
	v_lshl_add_u64 v[2:3], v[2:3], 0, v[182:183]
	v_readlane_b32 s2, v254, 40
	v_lshlrev_b64 v[10:11], 1, v[2:3]
	v_readlane_b32 s3, v254, 41
	s_nop 0
	v_cvt_pk_bf16_f32 v6, v26, v27
	s_nop 0
	v_cvt_pk_bf16_f32 v7, v28, v29
	v_pk_add_f32 v[24:25], v[12:13], v[44:45]
	v_pk_add_f32 v[20:21], v[8:9], v[40:41]
	v_lshl_add_u64 v[2:3], s[2:3], 0, v[10:11]
	global_store_dwordx2 v[2:3], v[6:7], off
	v_mul_f32_e32 v2, v27, v27
	v_mul_f32_e32 v3, v29, v29
	v_fmac_f32_e32 v2, v26, v26
	v_fmac_f32_e32 v3, v28, v28
	v_or_b32_e32 v6, 32, v10
	v_mov_b32_e32 v7, v11
	v_add_f32_e32 v16, v2, v3
	global_store_dwordx4 v[74:75], v[22:25], off offset:1024
	s_nop 0
	v_cvt_pk_bf16_f32 v2, v22, v23
	s_nop 0
	v_cvt_pk_bf16_f32 v3, v24, v25
	v_lshl_add_u64 v[6:7], s[2:3], 0, v[6:7]
	global_store_dwordx2 v[6:7], v[2:3], off
	v_mul_f32_e32 v2, v23, v23
	v_mul_f32_e32 v3, v25, v25
	v_fmac_f32_e32 v2, v22, v22
	v_fmac_f32_e32 v3, v24, v24
	v_add_f32_e32 v2, v2, v3
	v_add_f32_e32 v2, v16, v2
	v_mul_f32_e32 v3, v19, v19
	v_mul_f32_e32 v16, v21, v21
	v_fmac_f32_e32 v3, v18, v18
	v_fmac_f32_e32 v16, v20, v20
	v_add_f32_e32 v3, v3, v16
	v_pk_add_f32 v[16:17], v[4:5], v[36:37]
	v_add_f32_e32 v2, v2, v3
	v_mul_f32_e32 v3, v15, v15
	v_mul_f32_e32 v32, v17, v17
	v_fmac_f32_e32 v3, v14, v14
	v_fmac_f32_e32 v32, v16, v16
	v_add_f32_e32 v3, v3, v32
	v_and_b32_e32 v32, 64, v195
	v_add_f32_e32 v3, v2, v3
	v_xor_b32_e32 v2, 16, v195
	v_add_u32_e32 v32, 64, v32
	v_cmp_lt_i32_e32 vcc, v2, v32
	v_or_b32_e32 v30, 0x100, v10
	v_mov_b32_e32 v31, v11
	v_cndmask_b32_e32 v2, v195, v2, vcc
	v_lshlrev_b32_e32 v2, 2, v2
	ds_bpermute_b32 v33, v2, v3
	global_store_dwordx4 v[74:75], v[18:21], off offset:2048
	s_nop 0
	v_cvt_pk_bf16_f32 v6, v18, v19
	s_nop 0
	v_cvt_pk_bf16_f32 v7, v20, v21
	v_lshl_add_u64 v[30:31], s[2:3], 0, v[30:31]
	global_store_dwordx2 v[30:31], v[6:7], off
	global_store_dwordx4 v[74:75], v[14:17], off offset:3072
	s_waitcnt lgkmcnt(0)
	v_add_f32_e32 v6, v3, v33
	v_xor_b32_e32 v3, 32, v195
	v_cmp_lt_i32_e32 vcc, v3, v32
	v_or_b32_e32 v10, 0x120, v10
	v_lshl_add_u64 v[10:11], s[2:3], 0, v[10:11]
	v_cndmask_b32_e32 v3, v195, v3, vcc
	v_lshlrev_b32_e32 v3, 2, v3
	ds_bpermute_b32 v7, v3, v6
	s_nop 0
	v_cvt_pk_bf16_f32 v30, v14, v15
	s_nop 0
	v_cvt_pk_bf16_f32 v31, v16, v17
	global_store_dwordx2 v[10:11], v[30:31], off
	s_and_saveexec_b64 s[2:3], s[6:7]
	s_cbranch_execz .LBB0_2147
	v_lshl_add_u64 v[10:11], v[76:77], 2, s[10:11]
	s_waitcnt lgkmcnt(0)
	v_add_f32_e32 v6, v6, v7
	global_atomic_add_f32 v[10:11], v6, off

; __device__ __forceinline__ f32x4 sig4(const f32x4 v) { return (f32x4){sigmoidf_(v[0]), sigmoidf_(v[1]), sigmoidf_(v[2]), sigmoidf_(v[3])}; }
;     __device__ __forceinline__ void operator()(const typename AccT<I8>::type (&acc)[2][2][4][2], const Unit& u, int wr, int wc, int fr, int fq) const {
;     ...
;                     for (int n = 0; n < 2; ++n) { const size_t o = off + bj * HALF + n * 16; const f32x4 b = cur.b[bj][n]; f32x4 v;
;                         if constexpr (I8) v = __builtin_convertvector(acc[ai][bj][m][n], f32x4) * rs * sv[bj][n]; else v = acc[ai][bj][m][n];
;                         if (MODE == 1) { const u32x2 pw = cur.pw[bj][n]; const f32x4 pp = (f32x4){bf_lo(pw.x), bf_hi(pw.x), bf_lo(pw.y), bf_hi(pw.y)}; v = sig4(I8 ? v : v * rs) * pp; }
;                         const f32x4 x = b + v; *(f32x4*)(out + o) = x;
.LBB0_2150:
	v_pk_add_f32 v[24:25], v[12:13], v[44:45]
	v_pk_add_f32 v[20:21], v[8:9], v[40:41]
	v_pk_add_f32 v[16:17], v[4:5], v[36:37]
	global_store_dwordx4 v[74:75], v[22:25], off offset:1024
	global_store_dwordx4 v[74:75], v[18:21], off offset:2048
	global_store_dwordx4 v[74:75], v[14:17], off offset:3072

; #define PG8_STAGE(bufoff, gbase, voff) do { _Pragma("unroll") for (int _i = 0; _i < 2; ++_i) \
;         __builtin_amdgcn_global_load_lds((const unsigned*)((const char*)(gbase) + (voff)[_i]), (PG8_LAS unsigned*)(lds + (bufoff) + ldsw + _i * 8192), 16, 0, 0); } while (0)
; #define PG8_WAIT_V(n) asm volatile("s_waitcnt vmcnt(" #n ")" ::: "memory")
; #define PG8_BAR __builtin_amdgcn_s_barrier()
; template <class Epi, class Sched, bool ALIGN_EPI = false, bool SP2 = false, bool I8 = false>
; __device__ __forceinline__ void gemm_phase(PG8_LAS unsigned char* lds, const Gemm g, const Sched& S, const Epi& E) {
;     ...
;         PG8_STAGE(PG8_SB(0, 0), cB, voffB); PG8_STAGE(PG8_SB(0, 1), cB + hstepB, voffB); PG8_STAGE(PG8_SA(0, 0), cA, voffA); PG8_STAGE(PG8_SA(0, 1), cA + hstepA, voffA);
;         if (wr == 1) PG8_BAR;
;         PG8_WAIT_V(2); PG8_BAR;
;         PG8_STAGE(PG8_SB(1, 0), cB + kstep, voffB); PG8_STAGE(PG8_SA(1, 0), cA + kstep, voffA); PG8_STAGE(PG8_SB(1, 1), cB + hstepB + kstep, voffB);
;         PG8_WAIT_V(6); PG8_BAR;
; __global__ void __launch_bounds__(NWAVES * 64, 2) mk_fwd(Args args) {
;     ...
;         pg8::Gemm g{(const bf16*)(ws + WS_PB), (const bf16*)(ws + WS_WPLEP), M, D, PLE, PLE, PLE, 0}; pg8::StaticOrder S; S.init(M, D, F.G, bx);
;         pg8::EpiB<0> E{(bf16*)(ws + WS_PP), D, nullptr, nullptr, nullptr, nullptr};
;         pg8::gemm_phase<pg8::EpiB<0>, pg8::StaticOrder, true, true>(F.lds + RING_OFF, g, S, E);
.LBB0_2235:
	s_add_u32 s2, s96, 0x15400000
	s_addc_u32 s3, s97, 0
	s_lshl_b32 s6, s6, 12
	s_lshl_b32 s9, s7, 13
	s_and_b32 s12, s6, 0x3000
	s_mov_b64 s[6:7], 0x80
	s_add_i32 m0, s27, 0x18000
	v_lshl_add_u64 v[8:9], v[8:9], 0, s[6:7]
	s_waitcnt vmcnt(2)
	s_barrier
	global_load_lds_dwordx4 v[8:9], off
	v_lshl_add_u64 v[6:7], v[6:7], 0, s[6:7]
	s_add_i32 m0, s27, 0x1a000
	s_add_i32 s45, s27, 0x8000
	s_add_i32 s46, s27, 0xa000
	global_load_lds_dwordx4 v[6:7], off
	v_lshl_add_u64 v[2:3], v[2:3], 0, s[6:7]
	s_mov_b32 m0, s45
	s_add_u32 s10, s30, 0x10080
	global_load_lds_dwordx4 v[2:3], off
	v_lshl_add_u64 v[2:3], v[4:5], 0, s[6:7]
	s_mov_b32 m0, s46
	s_addc_u32 s11, s31, 0
	global_load_lds_dwordx4 v[2:3], off
	s_add_i32 m0, s27, 0x1c000
	v_lshl_add_u64 v[2:3], s[10:11], 0, v[132:133]
	global_load_lds_dwordx4 v[2:3], off
	v_lshl_add_u64 v[2:3], s[10:11], 0, v[136:137]
	s_add_i32 m0, s27, 0x1e000
	v_and_b32_e32 v1, 48, v0
	global_load_lds_dwordx4 v[2:3], off
	v_lshlrev_b32_e32 v2, 6, v0
	v_and_b32_e32 v2, 0x3c0, v2
	v_lshlrev_b32_e32 v4, 2, v0
	v_or_b32_e32 v3, v2, v1
	v_and_b32_e32 v4, 32, v4
	s_cmpk_lt_u32 s8, 0x100
	v_bitop3_b32 v1, v2, v4, v1 bitop3:0x36
	v_bitop3_b32 v2, s9, v3, v4 bitop3:0xf6
	s_cselect_b64 s[8:9], -1, 0
	s_ashr_i32 s47, s70, 31
	v_readlane_b32 s10, v254, 3
	s_waitcnt vmcnt(6)
	v_readlane_b32 s11, v254, 4
	s_add_u32 s10, s10, s70
	v_or_b32_e32 v1, s12, v1
	s_addc_u32 s11, s5, s47
	s_add_i32 s48, 0, 0x10000
	s_add_i32 s49, 0, 0x14000
	s_sext_i32_i8 s51, s4
	v_add_u32_e32 v146, s48, v1
	v_add_u32_e32 v147, s49, v1
	v_add_u32_e32 v148, 0, v2
	s_mov_b64 s[12:13], 0x100
	s_mov_b64 s[14:15], 0x180
	s_mov_b64 s[16:17], 0x100000
	s_mov_b32 s50, 0x100000
	s_barrier
	s_branch .LBB0_2238

; #define PG8_STAGE(bufoff, gbase, voff) do { _Pragma("unroll") for (int _i = 0; _i < 2; ++_i) \
;         __builtin_amdgcn_global_load_lds((const unsigned*)((const char*)(gbase) + (voff)[_i]), (PG8_LAS unsigned*)(lds + (bufoff) + ldsw + _i * 8192), 16, 0, 0); } while (0)
; #define PG8_WAIT_V(n) asm volatile("s_waitcnt vmcnt(" #n ")" ::: "memory")
; #define PG8_BAR __builtin_amdgcn_s_barrier()
; template <class Epi, class Sched, bool ALIGN_EPI = false, bool SP2 = false, bool I8 = false>
; __device__ __forceinline__ void gemm_phase(PG8_LAS unsigned char* lds, const Gemm g, const Sched& S, const Epi& E) {
;     ...
;         PG8_STAGE(PG8_SB(0, 0), cB, voffB); PG8_STAGE(PG8_SB(0, 1), cB + hstepB, voffB); PG8_STAGE(PG8_SA(0, 0), cA, voffA); PG8_STAGE(PG8_SA(0, 1), cA + hstepA, voffA);
;         if (wr == 1) PG8_BAR;
;         PG8_WAIT_V(2); PG8_BAR;
;         PG8_STAGE(PG8_SB(1, 0), cB + kstep, voffB); PG8_STAGE(PG8_SA(1, 0), cA + kstep, voffA); PG8_STAGE(PG8_SB(1, 1), cB + hstepB + kstep, voffB);
;         PG8_WAIT_V(6); PG8_BAR;
; __global__ void __launch_bounds__(NWAVES * 64, 2) mk_fwd(Args args) {
;     ...
;         pg8::Gemm g{(const bf16*)(ws + WS_X8D), (const bf16*)(ws + WS_W8P), M, D, D / 2, D / 2, D / 2, 0}; pg8::StaticOrder S; S.init(M, D, F.G, bx);
;         pg8::EpiF<1, true> E{F.out, F.out, (const float*)(ws + CTL_SS3), (const bf16*)(ws + WS_PP), nullptr, nullptr, nullptr, (const float*)(ws + WS_SX4), (const float*)(ws + WS_SWP)};
;         pg8::gemm_phase<pg8::EpiF<1, true>, pg8::StaticOrder, true, true, true>(F.lds + RING_OFF, g, S, E);
.LBB0_2312:
	s_add_u32 s6, s96, 0x60000
	s_addc_u32 s7, s97, 0
	s_add_u32 s8, s96, 0x15400000
	s_addc_u32 s9, s97, 0
	s_add_u32 s10, s96, 0x4d4c0000
	s_addc_u32 s11, s97, 0
	s_add_u32 s12, s96, 0x4d4a4000
	s_addc_u32 s13, s97, 0
	s_lshl_b32 s17, s14, 13
	s_mov_b64 s[14:15], 0x80
	s_lshl_b32 s1, s1, 12
	s_add_i32 m0, s3, 0x18000
	v_lshl_add_u64 v[8:9], v[8:9], 0, s[14:15]
	s_and_b32 s1, s1, 0x3000
	s_waitcnt vmcnt(2)
	s_barrier
	global_load_lds_dwordx4 v[8:9], off
	v_lshl_add_u64 v[6:7], v[6:7], 0, s[14:15]
	s_add_i32 m0, s3, 0x1a000
	s_add_i32 s43, s3, 0x8000
	s_add_i32 s44, s3, 0xa000
	global_load_lds_dwordx4 v[6:7], off
	v_lshl_add_u64 v[2:3], v[2:3], 0, s[14:15]
	s_mov_b32 m0, s43
	s_add_u32 s18, s28, 0x80080
	global_load_lds_dwordx4 v[2:3], off
	v_lshl_add_u64 v[2:3], v[4:5], 0, s[14:15]
	s_mov_b32 m0, s44
	s_addc_u32 s19, s29, 0
	global_load_lds_dwordx4 v[2:3], off
	s_add_i32 m0, s3, 0x1c000
	v_lshl_add_u64 v[2:3], s[18:19], 0, v[166:167]
	global_load_lds_dwordx4 v[2:3], off
	v_lshl_add_u64 v[2:3], s[18:19], 0, v[168:169]
	s_add_i32 m0, s3, 0x1e000
	v_and_b32_e32 v1, 48, v0
	global_load_lds_dwordx4 v[2:3], off
	v_lshlrev_b32_e32 v2, 6, v0
	v_and_b32_e32 v2, 0x3c0, v2
	v_lshlrev_b32_e32 v4, 2, v0
	v_or_b32_e32 v3, v2, v1
	v_and_b32_e32 v4, 32, v4
	v_bitop3_b32 v1, v2, v4, v1 bitop3:0x36
	v_bitop3_b32 v2, s17, v3, v4 bitop3:0xf6
	v_lshlrev_b32_e32 v3, 9, v0
	v_and_b32_e32 v3, 0x30000, v3
	v_lshlrev_b32_e32 v4, 12, v12
	v_or3_b32 v3, v10, v3, v4
	v_add_u32_e32 v170, v3, v11
	v_lshlrev_b32_e32 v3, 5, v13
	s_waitcnt vmcnt(6)
	s_cmpk_lt_u32 s16, 0x100
	v_and_b32_e32 v3, 0x70000, v3
	v_or_b32_e32 v1, s1, v1
	s_cselect_b64 s[16:17], -1, 0
	v_or3_b32 v3, v10, v3, v4
	s_add_i32 s46, 0, 0x10000
	s_add_i32 s47, 0, 0x14000
	s_sext_i32_i8 s48, s0
	s_ashr_i32 s45, s70, 31
	v_mov_b32_e32 v171, v167
	v_add_u32_e32 v172, v3, v11
	v_mov_b32_e32 v173, v167
	v_mov_b64_e32 v[174:175], 0x400
	v_mov_b64_e32 v[176:177], 0x3ff
	v_add_u32_e32 v183, s46, v1
	v_add_u32_e32 v189, s47, v1
	v_add_u32_e32 v193, 0, v2
	v_mov_b32_e32 v197, 0x358637bd
	s_barrier
	s_branch .LBB0_2315

;     __device__ __forceinline__ void operator()(const typename AccT<I8>::type (&acc)[2][2][4][2], const Unit& u, int wr, int wc, int fr, int fq) const {
;         const int row0 = u.pm * BM + wr * 64 + fr, col0 = u.pn * BM + wc * 32 + 4 * fq;
;         f32x4 sv[2][2];
;         if (I8) {
; #pragma unroll
;             for (int bj = 0; bj < 2; ++bj)
; #pragma unroll
;                 for (int n = 0; n < 2; ++n) sv[bj][n] = *(const f32x4*)(swc + col0 + bj * HALF + n * 16);
;         }
;         float rsv[8];
; #pragma unroll
;         for (int s = 0; s < 8; ++s) { const int r = row0 + (s >> 2) * HALF + (s & 3) * 16; float rs = 1.f; if (MODE == 1) rs = __builtin_amdgcn_rsqf(rstd[r] * (1.0f / 4096.0f) + 1e-6f); if (I8) rs *= sxr[r]; rsv[s] = rs; }
;         RowIn cur, nxt;
;         load_row(cur, (size_t)row0 * 4096 + col0);
; #pragma unroll
;         for (int s = 0; s < 8; ++s) { const int ai = s >> 2, m = s & 3; const int r = row0 + ai * HALF + m * 16; const size_t off = (size_t)r * 4096 + col0;
;                 if (s + 1 < 8) load_row(nxt, (size_t)(row0 + ((s + 1) >> 2) * HALF + ((s + 1) & 3) * 16) * 4096 + col0);
;                 const float rs = rsv[s];
;                 float ss = 0.f, mx = 0.f;
; #pragma unroll
;                 for (int bj = 0; bj < 2; ++bj)
; #pragma unroll
;                     for (int n = 0; n < 2; ++n) { const size_t o = off + bj * HALF + n * 16; const f32x4 b = cur.b[bj][n]; f32x4 v;
;                         if constexpr (I8) v = __builtin_convertvector(acc[ai][bj][m][n], f32x4) * rs * sv[bj][n]; else v = acc[ai][bj][m][n];
;                         if (MODE == 1) { const u32x2 pw = cur.pw[bj][n]; const f32x4 pp = (f32x4){bf_lo(pw.x), bf_hi(pw.x), bf_lo(pw.y), bf_hi(pw.y)}; v = sig4(I8 ? v : v * rs) * pp; }
;                         const f32x4 x = b + v; *(f32x4*)(out + o) = x;
;                         if (MODE == 0 && XB) { u32x2 w; w.x = cvt_pk_bf16(x[0], x[1]); w.y = cvt_pk_bf16(x[2], x[3]); *(u32x2*)(XB + o) = w; ss += (x[0] * x[0] + x[1] * x[1]) + (x[2] * x[2] + x[3] * x[3]);
;                             if (RM) mx = fmaxf(fmaxf(mx, fmaxf(fabsf(x[0]), fabsf(x[1]))), fmaxf(fabsf(x[2]), fabsf(x[3]))); } }
;                 if (MODE == 0 && XB) { ss += __shfl_xor(ss, 16); ss += __shfl_xor(ss, 32); if (fq == 0) unsafeAtomicAdd(SS + r, ss);
.LBB0_2325:
	s_lshl_b32 s49, s2, 4
	s_add_i32 s49, s49, s48
	s_lshl_b32 s50, s49, 17
	s_add_u32 s50, s8, s50
	s_addc_u32 s51, s9, 0
	s_sub_i32 s53, s49, 888
	s_cmp_lt_u32 s49, 888
	s_cselect_b32 s52, s49, s53
	s_mov_b32 s53, 0x4200000
	s_cselect_b32 s53, 0x3f600000, s53
	s_lshl_b32 s52, s52, 18
	s_add_u32 s52, s52, s53
	s_add_u32 s52, s96, s52
	s_addc_u32 s53, s97, 0
	v_readlane_b32 s54, v254, 14
	v_readlane_b32 s55, v254, 15
	v_lshrrev_b32_e32 v194, 2, v0
	v_and_b32_e32 v194, 64, v194
	v_and_b32_e32 v195, 15, v0
	v_lshl_add_u32 v194, s2, 8, v194
	v_add_u32_e32 v194, v194, v195
	s_lshl_b32 s2, s48, 8
	v_lshrrev_b32_e32 v195, 1, v0
	v_and_b32_e32 v195, 0x60, v195
	v_lshrrev_b32_e32 v255, 2, v0
	v_and_b32_e32 v255, 12, v255
	v_or3_b32 v195, v195, s2, v255
	v_lshlrev_b32_e32 v190, 14, v194
	v_lshl_add_u32 v190, v195, 2, v190
	v_and_b32_e32 v191, 63, v0
	v_lshlrev_b32_e32 v191, 4, v191
	v_lshrrev_b32_e32 v255, 6, v0
	v_lshl_add_u32 v191, v255, 14, v191
	v_lshlrev_b32_e32 v194, 2, v194
	v_lshlrev_b32_e32 v195, 2, v195
	global_load_dword v242, v194, s[6:7] offset:0
	global_load_dword v243, v194, s[6:7] offset:64
	global_load_dword v244, v194, s[6:7] offset:128
	global_load_dword v245, v194, s[6:7] offset:192
	global_load_dword v246, v194, s[6:7] offset:512
	global_load_dword v247, v194, s[6:7] offset:576
	global_load_dword v248, v194, s[6:7] offset:640
	global_load_dword v249, v194, s[6:7] offset:704
	global_load_dword v250, v194, s[10:11] offset:0
	global_load_dword v251, v194, s[10:11] offset:64
	global_load_dword v252, v194, s[10:11] offset:128
	global_load_dword v253, v194, s[10:11] offset:192
	global_load_dword v182, v194, s[10:11] offset:512
	global_load_dword v188, v194, s[10:11] offset:576
	global_load_dword v192, v194, s[10:11] offset:640
	global_load_dword v196, v194, s[10:11] offset:704
	global_load_dwordx4 v[58:61], v195, s[12:13] offset:0
	global_load_dwordx4 v[66:69], v195, s[12:13] offset:64
	global_load_dwordx4 v[74:77], v195, s[12:13] offset:512
	global_load_dwordx4 v[78:81], v195, s[12:13] offset:576
	v_and_b32_e32 v195, 63, v0
	v_lshlrev_b32_e32 v195, 4, v195
	v_lshlrev_b32_e32 v194, 1, v191
	v_sub_u32_e32 v194, v194, v195
	global_load_dwordx4 v[146:149], v194, s[52:53] offset:0
	global_load_dwordx4 v[150:153], v194, s[52:53] offset:1024
	global_load_dwordx4 v[154:157], v194, s[52:53] offset:2048
	global_load_dwordx4 v[158:161], v194, s[52:53] offset:3072
	global_load_dwordx4 v[162:165], v191, s[50:51] offset:0
	global_load_dwordx4 v[178:181], v191, s[50:51] offset:1024
	v_and_b32_e32 v195, 63, v0
	v_lshlrev_b32_e32 v195, 4, v195
	v_lshlrev_b32_e32 v194, 1, v191
	v_sub_u32_e32 v194, v194, v195
	v_add_u32_e32 v194, 0x1000, v194
	v_add_u32_e32 v195, 0x800, v191
	global_load_dwordx4 v[198:201], v194, s[52:53] offset:0
	global_load_dwordx4 v[202:205], v194, s[52:53] offset:1024
	global_load_dwordx4 v[206:209], v194, s[52:53] offset:2048
	global_load_dwordx4 v[210:213], v194, s[52:53] offset:3072
	global_load_dwordx4 v[184:187], v195, s[50:51] offset:0
	global_load_dwordx4 v[214:217], v195, s[50:51] offset:1024
	v_and_b32_e32 v195, 63, v0
	v_lshlrev_b32_e32 v195, 4, v195
	v_lshlrev_b32_e32 v194, 1, v191
	v_sub_u32_e32 v194, v194, v195
	v_add_u32_e32 v194, 0x2000, v194
	v_add_u32_e32 v195, 0x1000, v191
	global_load_dwordx4 v[218:221], v194, s[52:53] offset:0
	global_load_dwordx4 v[222:225], v194, s[52:53] offset:1024
	global_load_dwordx4 v[226:229], v194, s[52:53] offset:2048
	global_load_dwordx4 v[230:233], v194, s[52:53] offset:3072
	global_load_dwordx4 v[234:237], v195, s[50:51] offset:0
	global_load_dwordx4 v[238:241], v195, s[50:51] offset:1024
	v_mov_b32_e32 v255, 0xbfb8aa3b
	v_cvt_f32_i32_e32 v142, v142
	v_cvt_f32_i32_e32 v143, v143
	v_cvt_f32_i32_e32 v144, v144
	v_cvt_f32_i32_e32 v145, v145
	v_cvt_f32_i32_e32 v138, v138
	v_cvt_f32_i32_e32 v139, v139
	v_cvt_f32_i32_e32 v140, v140
	v_cvt_f32_i32_e32 v141, v141
	v_cvt_f32_i32_e32 v134, v134
	v_cvt_f32_i32_e32 v135, v135
	v_cvt_f32_i32_e32 v136, v136
	v_cvt_f32_i32_e32 v137, v137
	v_cvt_f32_i32_e32 v130, v130
	v_cvt_f32_i32_e32 v131, v131
	v_cvt_f32_i32_e32 v132, v132
	v_cvt_f32_i32_e32 v133, v133
	v_cvt_f32_i32_e32 v126, v126
	v_cvt_f32_i32_e32 v127, v127
	v_cvt_f32_i32_e32 v128, v128
	v_cvt_f32_i32_e32 v129, v129
	v_cvt_f32_i32_e32 v122, v122
	v_cvt_f32_i32_e32 v123, v123
	v_cvt_f32_i32_e32 v124, v124
	v_cvt_f32_i32_e32 v125, v125
	v_cvt_f32_i32_e32 v118, v118
	v_cvt_f32_i32_e32 v119, v119
	v_cvt_f32_i32_e32 v120, v120
	v_cvt_f32_i32_e32 v121, v121
	v_cvt_f32_i32_e32 v114, v114
	v_cvt_f32_i32_e32 v115, v115
	v_cvt_f32_i32_e32 v116, v116
	v_cvt_f32_i32_e32 v117, v117
	v_cvt_f32_i32_e32 v110, v110
	v_cvt_f32_i32_e32 v111, v111
	v_cvt_f32_i32_e32 v112, v112
	v_cvt_f32_i32_e32 v113, v113
	v_cvt_f32_i32_e32 v106, v106
	v_cvt_f32_i32_e32 v107, v107
	v_cvt_f32_i32_e32 v108, v108
	v_cvt_f32_i32_e32 v109, v109
	v_cvt_f32_i32_e32 v102, v102
	v_cvt_f32_i32_e32 v103, v103
	v_cvt_f32_i32_e32 v104, v104
	v_cvt_f32_i32_e32 v105, v105
	v_cvt_f32_i32_e32 v98, v98
	v_cvt_f32_i32_e32 v99, v99
	v_cvt_f32_i32_e32 v100, v100
	v_cvt_f32_i32_e32 v101, v101
	v_cvt_f32_i32_e32 v94, v94
	v_cvt_f32_i32_e32 v95, v95
	v_cvt_f32_i32_e32 v96, v96
	v_cvt_f32_i32_e32 v97, v97
	v_cvt_f32_i32_e32 v90, v90
	v_cvt_f32_i32_e32 v91, v91
	v_cvt_f32_i32_e32 v92, v92
	v_cvt_f32_i32_e32 v93, v93
	v_cvt_f32_i32_e32 v86, v86
	v_cvt_f32_i32_e32 v87, v87
	v_cvt_f32_i32_e32 v88, v88
	v_cvt_f32_i32_e32 v89, v89
	v_cvt_f32_i32_e32 v82, v82
	v_cvt_f32_i32_e32 v83, v83
	v_cvt_f32_i32_e32 v84, v84
	v_cvt_f32_i32_e32 v85, v85
	v_cvt_f32_i32_e32 v70, v70
	v_cvt_f32_i32_e32 v71, v71
	v_cvt_f32_i32_e32 v72, v72
	v_cvt_f32_i32_e32 v73, v73
;     __device__ __forceinline__ void operator()(const typename AccT<I8>::type (&acc)[2][2][4][2], const Unit& u, int wr, int wc, int fr, int fq) const {
;         const int row0 = u.pm * BM + wr * 64 + fr, col0 = u.pn * BM + wc * 32 + 4 * fq;
;         f32x4 sv[2][2];
;         if (I8) {
; #pragma unroll
;             for (int bj = 0; bj < 2; ++bj)
; #pragma unroll
;                 for (int n = 0; n < 2; ++n) sv[bj][n] = *(const f32x4*)(swc + col0 + bj * HALF + n * 16);
;         }
;         float rsv[8];
; #pragma unroll
;         for (int s = 0; s < 8; ++s) { const int r = row0 + (s >> 2) * HALF + (s & 3) * 16; float rs = 1.f; if (MODE == 1) rs = __builtin_amdgcn_rsqf(rstd[r] * (1.0f / 4096.0f) + 1e-6f); if (I8) rs *= sxr[r]; rsv[s] = rs; }
;         RowIn cur, nxt;
;         load_row(cur, (size_t)row0 * 4096 + col0);
; #pragma unroll
;         for (int s = 0; s < 8; ++s) { const int ai = s >> 2, m = s & 3; const int r = row0 + ai * HALF + m * 16; const size_t off = (size_t)r * 4096 + col0;
;                 if (s + 1 < 8) load_row(nxt, (size_t)(row0 + ((s + 1) >> 2) * HALF + ((s + 1) & 3) * 16) * 4096 + col0);
;                 const float rs = rsv[s];
;                 float ss = 0.f, mx = 0.f;
; #pragma unroll
;                 for (int bj = 0; bj < 2; ++bj)
; #pragma unroll
;                     for (int n = 0; n < 2; ++n) { const size_t o = off + bj * HALF + n * 16; const f32x4 b = cur.b[bj][n]; f32x4 v;
;                         if constexpr (I8) v = __builtin_convertvector(acc[ai][bj][m][n], f32x4) * rs * sv[bj][n]; else v = acc[ai][bj][m][n];
;                         if (MODE == 1) { const u32x2 pw = cur.pw[bj][n]; const f32x4 pp = (f32x4){bf_lo(pw.x), bf_hi(pw.x), bf_lo(pw.y), bf_hi(pw.y)}; v = sig4(I8 ? v : v * rs) * pp; }
;                         const f32x4 x = b + v; *(f32x4*)(out + o) = x;
;                         if (MODE == 0 && XB) { u32x2 w; w.x = cvt_pk_bf16(x[0], x[1]); w.y = cvt_pk_bf16(x[2], x[3]); *(u32x2*)(XB + o) = w; ss += (x[0] * x[0] + x[1] * x[1]) + (x[2] * x[2] + x[3] * x[3]);
;                             if (RM) mx = fmaxf(fmaxf(mx, fmaxf(fabsf(x[0]), fabsf(x[1]))), fmaxf(fabsf(x[2]), fabsf(x[3]))); } }
;                 if (MODE == 0 && XB) { ss += __shfl_xor(ss, 16); ss += __shfl_xor(ss, 32); if (fq == 0) unsafeAtomicAdd(SS + r, ss);
	v_cvt_f32_i32_e32 v62, v62
	v_cvt_f32_i32_e32 v63, v63
	v_cvt_f32_i32_e32 v64, v64
	v_cvt_f32_i32_e32 v65, v65
	v_cvt_f32_i32_e32 v54, v54
	v_cvt_f32_i32_e32 v55, v55
	v_cvt_f32_i32_e32 v56, v56
	v_cvt_f32_i32_e32 v57, v57
	v_cvt_f32_i32_e32 v50, v50
	v_cvt_f32_i32_e32 v51, v51
	v_cvt_f32_i32_e32 v52, v52
	v_cvt_f32_i32_e32 v53, v53
	v_cvt_f32_i32_e32 v46, v46
	v_cvt_f32_i32_e32 v47, v47
	v_cvt_f32_i32_e32 v48, v48
	v_cvt_f32_i32_e32 v49, v49
	v_cvt_f32_i32_e32 v42, v42
	v_cvt_f32_i32_e32 v43, v43
	v_cvt_f32_i32_e32 v44, v44
	v_cvt_f32_i32_e32 v45, v45
	v_cvt_f32_i32_e32 v38, v38
	v_cvt_f32_i32_e32 v39, v39
	v_cvt_f32_i32_e32 v40, v40
	v_cvt_f32_i32_e32 v41, v41
	v_cvt_f32_i32_e32 v34, v34
	v_cvt_f32_i32_e32 v35, v35
	v_cvt_f32_i32_e32 v36, v36
	v_cvt_f32_i32_e32 v37, v37
	v_cvt_f32_i32_e32 v30, v30
	v_cvt_f32_i32_e32 v31, v31
	v_cvt_f32_i32_e32 v32, v32
	v_cvt_f32_i32_e32 v33, v33
	v_cvt_f32_i32_e32 v26, v26
	v_cvt_f32_i32_e32 v27, v27
	v_cvt_f32_i32_e32 v28, v28
	v_cvt_f32_i32_e32 v29, v29
	v_cvt_f32_i32_e32 v22, v22
	v_cvt_f32_i32_e32 v23, v23
	v_cvt_f32_i32_e32 v24, v24
	v_cvt_f32_i32_e32 v25, v25
	v_cvt_f32_i32_e32 v18, v18
	v_cvt_f32_i32_e32 v19, v19
	v_cvt_f32_i32_e32 v20, v20
	v_cvt_f32_i32_e32 v21, v21
	v_cvt_f32_i32_e32 v14, v14
	v_cvt_f32_i32_e32 v15, v15
	v_cvt_f32_i32_e32 v16, v16
	v_cvt_f32_i32_e32 v17, v17
	v_cvt_f32_i32_e32 v10, v10
	v_cvt_f32_i32_e32 v11, v11
	v_cvt_f32_i32_e32 v12, v12
	v_cvt_f32_i32_e32 v13, v13
	v_cvt_f32_i32_e32 v6, v6
	v_cvt_f32_i32_e32 v7, v7
	v_cvt_f32_i32_e32 v8, v8
	v_cvt_f32_i32_e32 v9, v9
	v_cvt_f32_i32_e32 v2, v2
	v_cvt_f32_i32_e32 v3, v3
	v_cvt_f32_i32_e32 v4, v4
	v_cvt_f32_i32_e32 v5, v5
	s_waitcnt vmcnt(22)
	v_fmamk_f32 v242, v242, 0x39800000, v197
	v_fmamk_f32 v243, v243, 0x39800000, v197
	v_fmamk_f32 v244, v244, 0x39800000, v197
	v_fmamk_f32 v245, v245, 0x39800000, v197
	v_fmamk_f32 v246, v246, 0x39800000, v197
	v_fmamk_f32 v247, v247, 0x39800000, v197
	v_fmamk_f32 v248, v248, 0x39800000, v197
	v_fmamk_f32 v249, v249, 0x39800000, v197
	v_rsq_f32_e32 v242, v242
	v_rsq_f32_e32 v243, v243
	v_rsq_f32_e32 v244, v244
	v_rsq_f32_e32 v245, v245
	v_rsq_f32_e32 v246, v246
	v_rsq_f32_e32 v247, v247
	v_rsq_f32_e32 v248, v248
	v_rsq_f32_e32 v249, v249
	v_mul_f32_e32 v242, v250, v242
	v_mul_f32_e32 v243, v251, v243
	v_mul_f32_e32 v244, v252, v244
	v_mul_f32_e32 v245, v253, v245
	v_mul_f32_e32 v246, v182, v246
	v_mul_f32_e32 v247, v188, v247
	v_mul_f32_e32 v248, v192, v248
	v_mul_f32_e32 v249, v196, v249
	s_waitcnt vmcnt(18)
	v_pk_mul_f32 v[142:143], v[242:243], v[142:143] op_sel:[0,0] op_sel_hi:[0,1]
	v_pk_mul_f32 v[144:145], v[242:243], v[144:145] op_sel:[0,0] op_sel_hi:[0,1]
	v_pk_mul_f32 v[142:143], v[58:59], v[142:143]
	v_pk_mul_f32 v[144:145], v[60:61], v[144:145]
	v_mul_f32_e32 v142, v255, v142
	v_mul_f32_e32 v143, v255, v143
	v_mul_f32_e32 v144, v255, v144
	v_mul_f32_e32 v145, v255, v145
	v_exp_f32_e32 v142, v142
	v_exp_f32_e32 v143, v143
	v_exp_f32_e32 v144, v144
	v_exp_f32_e32 v145, v145
	v_add_f32_e32 v142, 1.0, v142
	v_add_f32_e32 v143, 1.0, v143
	v_add_f32_e32 v144, 1.0, v144
	v_add_f32_e32 v145, 1.0, v145
	v_rcp_f32_e32 v142, v142
	v_rcp_f32_e32 v143, v143
	v_rcp_f32_e32 v144, v144
	v_rcp_f32_e32 v145, v145
	s_waitcnt vmcnt(13)
	v_lshlrev_b32_e32 v250, 16, v162
	v_and_b32_e32 v251, 0xffff0000, v162
	v_lshlrev_b32_e32 v252, 16, v163
	v_and_b32_e32 v253, 0xffff0000, v163
	v_pk_fma_f32 v[146:147], v[142:143], v[250:251], v[146:147]
	v_pk_fma_f32 v[148:149], v[144:145], v[252:253], v[148:149]
	global_store_dwordx4 v190, v[146:149], s[54:55] offset:0
	v_pk_mul_f32 v[138:139], v[242:243], v[138:139] op_sel:[0,0] op_sel_hi:[0,1]
	v_pk_mul_f32 v[140:141], v[242:243], v[140:141] op_sel:[0,0] op_sel_hi:[0,1]
	v_pk_mul_f32 v[138:139], v[66:67], v[138:139]
	v_pk_mul_f32 v[140:141], v[68:69], v[140:141]
	v_mul_f32_e32 v138, v255, v138
	v_mul_f32_e32 v139, v255, v139
	v_mul_f32_e32 v140, v255, v140
	v_mul_f32_e32 v141, v255, v141
	v_exp_f32_e32 v138, v138
	v_exp_f32_e32 v139, v139
	v_exp_f32_e32 v140, v140
	v_exp_f32_e32 v141, v141
	v_add_f32_e32 v138, 1.0, v138
	v_add_f32_e32 v139, 1.0, v139
	v_add_f32_e32 v140, 1.0, v140
	v_add_f32_e32 v141, 1.0, v141
	v_rcp_f32_e32 v138, v138
	v_rcp_f32_e32 v139, v139
	v_rcp_f32_e32 v140, v140
	v_rcp_f32_e32 v141, v141
	v_lshlrev_b32_e32 v250, 16, v164
	v_and_b32_e32 v251, 0xffff0000, v164
	v_lshlrev_b32_e32 v252, 16, v165
	v_and_b32_e32 v253, 0xffff0000, v165
	v_pk_fma_f32 v[150:151], v[138:139], v[250:251], v[150:151]
	v_pk_fma_f32 v[152:153], v[140:141], v[252:253], v[152:153]
	global_store_dwordx4 v190, v[150:153], s[54:55] offset:64
	v_pk_mul_f32 v[134:135], v[242:243], v[134:135] op_sel:[0,0] op_sel_hi:[0,1]
	v_pk_mul_f32 v[136:137], v[242:243], v[136:137] op_sel:[0,0] op_sel_hi:[0,1]
	v_pk_mul_f32 v[134:135], v[74:75], v[134:135]
	v_pk_mul_f32 v[136:137], v[76:77], v[136:137]
	v_mul_f32_e32 v134, v255, v134
	v_mul_f32_e32 v135, v255, v135
	v_mul_f32_e32 v136, v255, v136
	v_mul_f32_e32 v137, v255, v137
	v_exp_f32_e32 v134, v134
	v_exp_f32_e32 v135, v135
	v_exp_f32_e32 v136, v136
	v_exp_f32_e32 v137, v137
	v_add_f32_e32 v134, 1.0, v134
	v_add_f32_e32 v135, 1.0, v135
	v_add_f32_e32 v136, 1.0, v136
	v_add_f32_e32 v137, 1.0, v137
	v_rcp_f32_e32 v134, v134
	v_rcp_f32_e32 v135, v135
	v_rcp_f32_e32 v136, v136
	v_rcp_f32_e32 v137, v137
	s_waitcnt vmcnt(14)
;     __device__ __forceinline__ void operator()(const typename AccT<I8>::type (&acc)[2][2][4][2], const Unit& u, int wr, int wc, int fr, int fq) const {
;         const int row0 = u.pm * BM + wr * 64 + fr, col0 = u.pn * BM + wc * 32 + 4 * fq;
;         f32x4 sv[2][2];
;         if (I8) {
; #pragma unroll
;             for (int bj = 0; bj < 2; ++bj)
; #pragma unroll
;                 for (int n = 0; n < 2; ++n) sv[bj][n] = *(const f32x4*)(swc + col0 + bj * HALF + n * 16);
;         }
;         float rsv[8];
; #pragma unroll
;         for (int s = 0; s < 8; ++s) { const int r = row0 + (s >> 2) * HALF + (s & 3) * 16; float rs = 1.f; if (MODE == 1) rs = __builtin_amdgcn_rsqf(rstd[r] * (1.0f / 4096.0f) + 1e-6f); if (I8) rs *= sxr[r]; rsv[s] = rs; }
;         RowIn cur, nxt;
;         load_row(cur, (size_t)row0 * 4096 + col0);
; #pragma unroll
;         for (int s = 0; s < 8; ++s) { const int ai = s >> 2, m = s & 3; const int r = row0 + ai * HALF + m * 16; const size_t off = (size_t)r * 4096 + col0;
;                 if (s + 1 < 8) load_row(nxt, (size_t)(row0 + ((s + 1) >> 2) * HALF + ((s + 1) & 3) * 16) * 4096 + col0);
;                 const float rs = rsv[s];
;                 float ss = 0.f, mx = 0.f;
; #pragma unroll
;                 for (int bj = 0; bj < 2; ++bj)
; #pragma unroll
;                     for (int n = 0; n < 2; ++n) { const size_t o = off + bj * HALF + n * 16; const f32x4 b = cur.b[bj][n]; f32x4 v;
;                         if constexpr (I8) v = __builtin_convertvector(acc[ai][bj][m][n], f32x4) * rs * sv[bj][n]; else v = acc[ai][bj][m][n];
;                         if (MODE == 1) { const u32x2 pw = cur.pw[bj][n]; const f32x4 pp = (f32x4){bf_lo(pw.x), bf_hi(pw.x), bf_lo(pw.y), bf_hi(pw.y)}; v = sig4(I8 ? v : v * rs) * pp; }
;                         const f32x4 x = b + v; *(f32x4*)(out + o) = x;
;                         if (MODE == 0 && XB) { u32x2 w; w.x = cvt_pk_bf16(x[0], x[1]); w.y = cvt_pk_bf16(x[2], x[3]); *(u32x2*)(XB + o) = w; ss += (x[0] * x[0] + x[1] * x[1]) + (x[2] * x[2] + x[3] * x[3]);
;                             if (RM) mx = fmaxf(fmaxf(mx, fmaxf(fabsf(x[0]), fabsf(x[1]))), fmaxf(fabsf(x[2]), fabsf(x[3]))); } }
;                 if (MODE == 0 && XB) { ss += __shfl_xor(ss, 16); ss += __shfl_xor(ss, 32); if (fq == 0) unsafeAtomicAdd(SS + r, ss);
	v_lshlrev_b32_e32 v250, 16, v178
	v_and_b32_e32 v251, 0xffff0000, v178
	v_lshlrev_b32_e32 v252, 16, v179
	v_and_b32_e32 v253, 0xffff0000, v179
	v_pk_fma_f32 v[154:155], v[134:135], v[250:251], v[154:155]
	v_pk_fma_f32 v[156:157], v[136:137], v[252:253], v[156:157]
	global_store_dwordx4 v190, v[154:157], s[54:55] offset:512
	v_pk_mul_f32 v[130:131], v[242:243], v[130:131] op_sel:[0,0] op_sel_hi:[0,1]
	v_pk_mul_f32 v[132:133], v[242:243], v[132:133] op_sel:[0,0] op_sel_hi:[0,1]
	v_pk_mul_f32 v[130:131], v[78:79], v[130:131]
	v_pk_mul_f32 v[132:133], v[80:81], v[132:133]
	v_mul_f32_e32 v130, v255, v130
	v_mul_f32_e32 v131, v255, v131
	v_mul_f32_e32 v132, v255, v132
	v_mul_f32_e32 v133, v255, v133
	v_exp_f32_e32 v130, v130
	v_exp_f32_e32 v131, v131
	v_exp_f32_e32 v132, v132
	v_exp_f32_e32 v133, v133
	v_add_f32_e32 v130, 1.0, v130
	v_add_f32_e32 v131, 1.0, v131
	v_add_f32_e32 v132, 1.0, v132
	v_add_f32_e32 v133, 1.0, v133
	v_rcp_f32_e32 v130, v130
	v_rcp_f32_e32 v131, v131
	v_rcp_f32_e32 v132, v132
	v_rcp_f32_e32 v133, v133
	v_lshlrev_b32_e32 v250, 16, v180
	v_and_b32_e32 v251, 0xffff0000, v180
	v_lshlrev_b32_e32 v252, 16, v181
	v_and_b32_e32 v253, 0xffff0000, v181
	v_pk_fma_f32 v[158:159], v[130:131], v[250:251], v[158:159]
	v_pk_fma_f32 v[160:161], v[132:133], v[252:253], v[160:161]
	global_store_dwordx4 v190, v[158:161], s[54:55] offset:576
	v_and_b32_e32 v195, 63, v0
	v_lshlrev_b32_e32 v195, 4, v195
	v_lshlrev_b32_e32 v194, 1, v191
	v_sub_u32_e32 v194, v194, v195
	v_add_u32_e32 v194, 0x3000, v194
	v_add_u32_e32 v195, 0x1800, v191
	global_load_dwordx4 v[146:149], v194, s[52:53] offset:0
	global_load_dwordx4 v[150:153], v194, s[52:53] offset:1024
	global_load_dwordx4 v[154:157], v194, s[52:53] offset:2048
	global_load_dwordx4 v[158:161], v194, s[52:53] offset:3072
	global_load_dwordx4 v[162:165], v195, s[50:51] offset:0
	global_load_dwordx4 v[178:181], v195, s[50:51] offset:1024
	v_add_u32_e32 v194, 0x40000, v190
	v_pk_mul_f32 v[126:127], v[242:243], v[126:127] op_sel:[1,0] op_sel_hi:[1,1]
	v_pk_mul_f32 v[128:129], v[242:243], v[128:129] op_sel:[1,0] op_sel_hi:[1,1]
	v_pk_mul_f32 v[126:127], v[58:59], v[126:127]
	v_pk_mul_f32 v[128:129], v[60:61], v[128:129]
	v_mul_f32_e32 v126, v255, v126
	v_mul_f32_e32 v127, v255, v127
	v_mul_f32_e32 v128, v255, v128
	v_mul_f32_e32 v129, v255, v129
	v_exp_f32_e32 v126, v126
	v_exp_f32_e32 v127, v127
	v_exp_f32_e32 v128, v128
	v_exp_f32_e32 v129, v129
	v_add_f32_e32 v126, 1.0, v126
	v_add_f32_e32 v127, 1.0, v127
	v_add_f32_e32 v128, 1.0, v128
	v_add_f32_e32 v129, 1.0, v129
	v_rcp_f32_e32 v126, v126
	v_rcp_f32_e32 v127, v127
	v_rcp_f32_e32 v128, v128
	v_rcp_f32_e32 v129, v129
	s_waitcnt vmcnt(17)
	v_lshlrev_b32_e32 v250, 16, v184
	v_and_b32_e32 v251, 0xffff0000, v184
	v_lshlrev_b32_e32 v252, 16, v185
	v_and_b32_e32 v253, 0xffff0000, v185
	v_pk_fma_f32 v[198:199], v[126:127], v[250:251], v[198:199]
	v_pk_fma_f32 v[200:201], v[128:129], v[252:253], v[200:201]
	global_store_dwordx4 v194, v[198:201], s[54:55] offset:0
	v_pk_mul_f32 v[122:123], v[242:243], v[122:123] op_sel:[1,0] op_sel_hi:[1,1]
	v_pk_mul_f32 v[124:125], v[242:243], v[124:125] op_sel:[1,0] op_sel_hi:[1,1]
	v_pk_mul_f32 v[122:123], v[66:67], v[122:123]
	v_pk_mul_f32 v[124:125], v[68:69], v[124:125]
	v_mul_f32_e32 v122, v255, v122
	v_mul_f32_e32 v123, v255, v123
	v_mul_f32_e32 v124, v255, v124
	v_mul_f32_e32 v125, v255, v125
	v_exp_f32_e32 v122, v122
	v_exp_f32_e32 v123, v123
	v_exp_f32_e32 v124, v124
	v_exp_f32_e32 v125, v125
	v_add_f32_e32 v122, 1.0, v122
	v_add_f32_e32 v123, 1.0, v123
	v_add_f32_e32 v124, 1.0, v124
	v_add_f32_e32 v125, 1.0, v125
	v_rcp_f32_e32 v122, v122
	v_rcp_f32_e32 v123, v123
	v_rcp_f32_e32 v124, v124
	v_rcp_f32_e32 v125, v125
	v_lshlrev_b32_e32 v250, 16, v186
	v_and_b32_e32 v251, 0xffff0000, v186
	v_lshlrev_b32_e32 v252, 16, v187
	v_and_b32_e32 v253, 0xffff0000, v187
	v_pk_fma_f32 v[202:203], v[122:123], v[250:251], v[202:203]
	v_pk_fma_f32 v[204:205], v[124:125], v[252:253], v[204:205]
	global_store_dwordx4 v194, v[202:205], s[54:55] offset:64
	v_pk_mul_f32 v[118:119], v[242:243], v[118:119] op_sel:[1,0] op_sel_hi:[1,1]
	v_pk_mul_f32 v[120:121], v[242:243], v[120:121] op_sel:[1,0] op_sel_hi:[1,1]
	v_pk_mul_f32 v[118:119], v[74:75], v[118:119]
	v_pk_mul_f32 v[120:121], v[76:77], v[120:121]
	v_mul_f32_e32 v118, v255, v118
	v_mul_f32_e32 v119, v255, v119
	v_mul_f32_e32 v120, v255, v120
	v_mul_f32_e32 v121, v255, v121
	v_exp_f32_e32 v118, v118
	v_exp_f32_e32 v119, v119
	v_exp_f32_e32 v120, v120
	v_exp_f32_e32 v121, v121
	v_add_f32_e32 v118, 1.0, v118
	v_add_f32_e32 v119, 1.0, v119
	v_add_f32_e32 v120, 1.0, v120
	v_add_f32_e32 v121, 1.0, v121
	v_rcp_f32_e32 v118, v118
	v_rcp_f32_e32 v119, v119
	v_rcp_f32_e32 v120, v120
	v_rcp_f32_e32 v121, v121
	s_waitcnt vmcnt(18)
; __device__ __forceinline__ f32x4 sig4(const f32x4 v) { return (f32x4){sigmoidf_(v[0]), sigmoidf_(v[1]), sigmoidf_(v[2]), sigmoidf_(v[3])}; }
;     __device__ __forceinline__ void load_row(RowIn& R, size_t off) const {
; #pragma unroll
;         for (int bj = 0; bj < 2; ++bj)
; #pragma unroll
;             for (int n = 0; n < 2; ++n) { const size_t o = off + bj * HALF + n * 16; R.b[bj][n] = *(const f32x4*)(res + o); if (MODE == 1) R.pw[bj][n] = *(const u32x2*)(PP + o); }
;     __device__ __forceinline__ void operator()(const typename AccT<I8>::type (&acc)[2][2][4][2], const Unit& u, int wr, int wc, int fr, int fq) const {
;     ...
;         for (int s = 0; s < 8; ++s) { const int ai = s >> 2, m = s & 3; const int r = row0 + ai * HALF + m * 16; const size_t off = (size_t)r * 4096 + col0;
;                 if (s + 1 < 8) load_row(nxt, (size_t)(row0 + ((s + 1) >> 2) * HALF + ((s + 1) & 3) * 16) * 4096 + col0);
;                 const float rs = rsv[s];
;                 float ss = 0.f, mx = 0.f;
; #pragma unroll
;                 for (int bj = 0; bj < 2; ++bj)
; #pragma unroll
;                     for (int n = 0; n < 2; ++n) { const size_t o = off + bj * HALF + n * 16; const f32x4 b = cur.b[bj][n]; f32x4 v;
;                         if constexpr (I8) v = __builtin_convertvector(acc[ai][bj][m][n], f32x4) * rs * sv[bj][n]; else v = acc[ai][bj][m][n];
;                         if (MODE == 1) { const u32x2 pw = cur.pw[bj][n]; const f32x4 pp = (f32x4){bf_lo(pw.x), bf_hi(pw.x), bf_lo(pw.y), bf_hi(pw.y)}; v = sig4(I8 ? v : v * rs) * pp; }
;                         const f32x4 x = b + v; *(f32x4*)(out + o) = x;
	v_lshlrev_b32_e32 v250, 16, v214
	v_and_b32_e32 v251, 0xffff0000, v214
	v_lshlrev_b32_e32 v252, 16, v215
	v_and_b32_e32 v253, 0xffff0000, v215
	v_pk_fma_f32 v[206:207], v[118:119], v[250:251], v[206:207]
	v_pk_fma_f32 v[208:209], v[120:121], v[252:253], v[208:209]
	global_store_dwordx4 v194, v[206:209], s[54:55] offset:512
	v_pk_mul_f32 v[114:115], v[242:243], v[114:115] op_sel:[1,0] op_sel_hi:[1,1]
	v_pk_mul_f32 v[116:117], v[242:243], v[116:117] op_sel:[1,0] op_sel_hi:[1,1]
	v_pk_mul_f32 v[114:115], v[78:79], v[114:115]
	v_pk_mul_f32 v[116:117], v[80:81], v[116:117]
	v_mul_f32_e32 v114, v255, v114
	v_mul_f32_e32 v115, v255, v115
	v_mul_f32_e32 v116, v255, v116
	v_mul_f32_e32 v117, v255, v117
	v_exp_f32_e32 v114, v114
	v_exp_f32_e32 v115, v115
	v_exp_f32_e32 v116, v116
	v_exp_f32_e32 v117, v117
	v_add_f32_e32 v114, 1.0, v114
	v_add_f32_e32 v115, 1.0, v115
	v_add_f32_e32 v116, 1.0, v116
	v_add_f32_e32 v117, 1.0, v117
	v_rcp_f32_e32 v114, v114
	v_rcp_f32_e32 v115, v115
	v_rcp_f32_e32 v116, v116
	v_rcp_f32_e32 v117, v117
	v_lshlrev_b32_e32 v250, 16, v216
	v_and_b32_e32 v251, 0xffff0000, v216
	v_lshlrev_b32_e32 v252, 16, v217
	v_and_b32_e32 v253, 0xffff0000, v217
	v_pk_fma_f32 v[210:211], v[114:115], v[250:251], v[210:211]
	v_pk_fma_f32 v[212:213], v[116:117], v[252:253], v[212:213]
	global_store_dwordx4 v194, v[210:213], s[54:55] offset:576
	v_and_b32_e32 v195, 63, v0
	v_lshlrev_b32_e32 v195, 4, v195
	v_lshlrev_b32_e32 v194, 1, v191
	v_sub_u32_e32 v194, v194, v195
	v_add_u32_e32 v194, 0x4000, v194
	v_add_u32_e32 v195, 0x2000, v191
	global_load_dwordx4 v[198:201], v194, s[52:53] offset:0
	global_load_dwordx4 v[202:205], v194, s[52:53] offset:1024
	global_load_dwordx4 v[206:209], v194, s[52:53] offset:2048
	global_load_dwordx4 v[210:213], v194, s[52:53] offset:3072
	global_load_dwordx4 v[184:187], v195, s[50:51] offset:0
	global_load_dwordx4 v[214:217], v195, s[50:51] offset:1024
	v_and_b32_e32 v195, 63, v0
	v_lshlrev_b32_e32 v195, 4, v195
	v_lshlrev_b32_e32 v194, 1, v191
	v_sub_u32_e32 v194, v194, v195
	v_add_u32_e32 v194, 0x5000, v194
	v_add_u32_e32 v195, 0x2800, v191
	global_load_dwordx4 v[142:145], v194, s[52:53] offset:0
	global_load_dwordx4 v[138:141], v194, s[52:53] offset:1024
	global_load_dwordx4 v[134:137], v194, s[52:53] offset:2048
	global_load_dwordx4 v[130:133], v194, s[52:53] offset:3072
	global_load_dwordx4 v[126:129], v195, s[50:51] offset:0
	global_load_dwordx4 v[122:125], v195, s[50:51] offset:1024
	v_add_u32_e32 v194, 0x80000, v190
	v_pk_mul_f32 v[110:111], v[244:245], v[110:111] op_sel:[0,0] op_sel_hi:[0,1]
	v_pk_mul_f32 v[112:113], v[244:245], v[112:113] op_sel:[0,0] op_sel_hi:[0,1]
	v_pk_mul_f32 v[110:111], v[58:59], v[110:111]
	v_pk_mul_f32 v[112:113], v[60:61], v[112:113]
	v_mul_f32_e32 v110, v255, v110
	v_mul_f32_e32 v111, v255, v111
	v_mul_f32_e32 v112, v255, v112
	v_mul_f32_e32 v113, v255, v113
	v_exp_f32_e32 v110, v110
	v_exp_f32_e32 v111, v111
	v_exp_f32_e32 v112, v112
	v_exp_f32_e32 v113, v113
	v_add_f32_e32 v110, 1.0, v110
	v_add_f32_e32 v111, 1.0, v111
	v_add_f32_e32 v112, 1.0, v112
	v_add_f32_e32 v113, 1.0, v113
	v_rcp_f32_e32 v110, v110
	v_rcp_f32_e32 v111, v111
	v_rcp_f32_e32 v112, v112
	v_rcp_f32_e32 v113, v113
	s_waitcnt vmcnt(27)
	v_lshlrev_b32_e32 v250, 16, v234
	v_and_b32_e32 v251, 0xffff0000, v234
	v_lshlrev_b32_e32 v252, 16, v235
	v_and_b32_e32 v253, 0xffff0000, v235
	v_pk_fma_f32 v[218:219], v[110:111], v[250:251], v[218:219]
	v_pk_fma_f32 v[220:221], v[112:113], v[252:253], v[220:221]
	global_store_dwordx4 v194, v[218:221], s[54:55] offset:0
	v_pk_mul_f32 v[106:107], v[244:245], v[106:107] op_sel:[0,0] op_sel_hi:[0,1]
	v_pk_mul_f32 v[108:109], v[244:245], v[108:109] op_sel:[0,0] op_sel_hi:[0,1]
	v_pk_mul_f32 v[106:107], v[66:67], v[106:107]
	v_pk_mul_f32 v[108:109], v[68:69], v[108:109]
	v_mul_f32_e32 v106, v255, v106
	v_mul_f32_e32 v107, v255, v107
	v_mul_f32_e32 v108, v255, v108
	v_mul_f32_e32 v109, v255, v109
	v_exp_f32_e32 v106, v106
	v_exp_f32_e32 v107, v107
	v_exp_f32_e32 v108, v108
	v_exp_f32_e32 v109, v109
	v_add_f32_e32 v106, 1.0, v106
	v_add_f32_e32 v107, 1.0, v107
	v_add_f32_e32 v108, 1.0, v108
	v_add_f32_e32 v109, 1.0, v109
	v_rcp_f32_e32 v106, v106
	v_rcp_f32_e32 v107, v107
	v_rcp_f32_e32 v108, v108
	v_rcp_f32_e32 v109, v109
	v_lshlrev_b32_e32 v250, 16, v236
	v_and_b32_e32 v251, 0xffff0000, v236
	v_lshlrev_b32_e32 v252, 16, v237
	v_and_b32_e32 v253, 0xffff0000, v237
	v_pk_fma_f32 v[222:223], v[106:107], v[250:251], v[222:223]
	v_pk_fma_f32 v[224:225], v[108:109], v[252:253], v[224:225]
	global_store_dwordx4 v194, v[222:225], s[54:55] offset:64
	v_pk_mul_f32 v[102:103], v[244:245], v[102:103] op_sel:[0,0] op_sel_hi:[0,1]
	v_pk_mul_f32 v[104:105], v[244:245], v[104:105] op_sel:[0,0] op_sel_hi:[0,1]
	v_pk_mul_f32 v[102:103], v[74:75], v[102:103]
	v_pk_mul_f32 v[104:105], v[76:77], v[104:105]
	v_mul_f32_e32 v102, v255, v102
	v_mul_f32_e32 v103, v255, v103
	v_mul_f32_e32 v104, v255, v104
	v_mul_f32_e32 v105, v255, v105
	v_exp_f32_e32 v102, v102
	v_exp_f32_e32 v103, v103
	v_exp_f32_e32 v104, v104
	v_exp_f32_e32 v105, v105
	v_add_f32_e32 v102, 1.0, v102
	v_add_f32_e32 v103, 1.0, v103
	v_add_f32_e32 v104, 1.0, v104
	v_add_f32_e32 v105, 1.0, v105
	v_rcp_f32_e32 v102, v102
	v_rcp_f32_e32 v103, v103
	v_rcp_f32_e32 v104, v104
	v_rcp_f32_e32 v105, v105
	s_waitcnt vmcnt(28)
; __device__ __forceinline__ f32x4 sig4(const f32x4 v) { return (f32x4){sigmoidf_(v[0]), sigmoidf_(v[1]), sigmoidf_(v[2]), sigmoidf_(v[3])}; }
;     __device__ __forceinline__ void load_row(RowIn& R, size_t off) const {
; #pragma unroll
;         for (int bj = 0; bj < 2; ++bj)
; #pragma unroll
;             for (int n = 0; n < 2; ++n) { const size_t o = off + bj * HALF + n * 16; R.b[bj][n] = *(const f32x4*)(res + o); if (MODE == 1) R.pw[bj][n] = *(const u32x2*)(PP + o); }
;     __device__ __forceinline__ void operator()(const typename AccT<I8>::type (&acc)[2][2][4][2], const Unit& u, int wr, int wc, int fr, int fq) const {
;     ...
;         for (int s = 0; s < 8; ++s) { const int ai = s >> 2, m = s & 3; const int r = row0 + ai * HALF + m * 16; const size_t off = (size_t)r * 4096 + col0;
;                 if (s + 1 < 8) load_row(nxt, (size_t)(row0 + ((s + 1) >> 2) * HALF + ((s + 1) & 3) * 16) * 4096 + col0);
;                 const float rs = rsv[s];
;                 float ss = 0.f, mx = 0.f;
; #pragma unroll
;                 for (int bj = 0; bj < 2; ++bj)
; #pragma unroll
;                     for (int n = 0; n < 2; ++n) { const size_t o = off + bj * HALF + n * 16; const f32x4 b = cur.b[bj][n]; f32x4 v;
;                         if constexpr (I8) v = __builtin_convertvector(acc[ai][bj][m][n], f32x4) * rs * sv[bj][n]; else v = acc[ai][bj][m][n];
;                         if (MODE == 1) { const u32x2 pw = cur.pw[bj][n]; const f32x4 pp = (f32x4){bf_lo(pw.x), bf_hi(pw.x), bf_lo(pw.y), bf_hi(pw.y)}; v = sig4(I8 ? v : v * rs) * pp; }
;                         const f32x4 x = b + v; *(f32x4*)(out + o) = x;
	v_lshlrev_b32_e32 v250, 16, v238
	v_and_b32_e32 v251, 0xffff0000, v238
	v_lshlrev_b32_e32 v252, 16, v239
	v_and_b32_e32 v253, 0xffff0000, v239
	v_pk_fma_f32 v[226:227], v[102:103], v[250:251], v[226:227]
	v_pk_fma_f32 v[228:229], v[104:105], v[252:253], v[228:229]
	global_store_dwordx4 v194, v[226:229], s[54:55] offset:512
	v_pk_mul_f32 v[98:99], v[244:245], v[98:99] op_sel:[0,0] op_sel_hi:[0,1]
	v_pk_mul_f32 v[100:101], v[244:245], v[100:101] op_sel:[0,0] op_sel_hi:[0,1]
	v_pk_mul_f32 v[98:99], v[78:79], v[98:99]
	v_pk_mul_f32 v[100:101], v[80:81], v[100:101]
	v_mul_f32_e32 v98, v255, v98
	v_mul_f32_e32 v99, v255, v99
	v_mul_f32_e32 v100, v255, v100
	v_mul_f32_e32 v101, v255, v101
	v_exp_f32_e32 v98, v98
	v_exp_f32_e32 v99, v99
	v_exp_f32_e32 v100, v100
	v_exp_f32_e32 v101, v101
	v_add_f32_e32 v98, 1.0, v98
	v_add_f32_e32 v99, 1.0, v99
	v_add_f32_e32 v100, 1.0, v100
	v_add_f32_e32 v101, 1.0, v101
	v_rcp_f32_e32 v98, v98
	v_rcp_f32_e32 v99, v99
	v_rcp_f32_e32 v100, v100
	v_rcp_f32_e32 v101, v101
	v_lshlrev_b32_e32 v250, 16, v240
	v_and_b32_e32 v251, 0xffff0000, v240
	v_lshlrev_b32_e32 v252, 16, v241
	v_and_b32_e32 v253, 0xffff0000, v241
	v_pk_fma_f32 v[230:231], v[98:99], v[250:251], v[230:231]
	v_pk_fma_f32 v[232:233], v[100:101], v[252:253], v[232:233]
	global_store_dwordx4 v194, v[230:233], s[54:55] offset:576
	v_and_b32_e32 v195, 63, v0
	v_lshlrev_b32_e32 v195, 4, v195
	v_lshlrev_b32_e32 v194, 1, v191
	v_sub_u32_e32 v194, v194, v195
	v_add_u32_e32 v194, 0x6000, v194
	v_add_u32_e32 v195, 0x3000, v191
	global_load_dwordx4 v[218:221], v194, s[52:53] offset:0
	global_load_dwordx4 v[222:225], v194, s[52:53] offset:1024
	global_load_dwordx4 v[226:229], v194, s[52:53] offset:2048
	global_load_dwordx4 v[230:233], v194, s[52:53] offset:3072
	global_load_dwordx4 v[234:237], v195, s[50:51] offset:0
	global_load_dwordx4 v[238:241], v195, s[50:51] offset:1024
	v_and_b32_e32 v195, 63, v0
	v_lshlrev_b32_e32 v195, 4, v195
	v_lshlrev_b32_e32 v194, 1, v191
	v_sub_u32_e32 v194, v194, v195
	v_add_u32_e32 v194, 0x7000, v194
	v_add_u32_e32 v195, 0x3800, v191
	global_load_dwordx4 v[110:113], v194, s[52:53] offset:0
	global_load_dwordx4 v[106:109], v194, s[52:53] offset:1024
	global_load_dwordx4 v[102:105], v194, s[52:53] offset:2048
	global_load_dwordx4 v[98:101], v194, s[52:53] offset:3072
	global_load_dwordx4 v[118:121], v195, s[50:51] offset:0
	global_load_dwordx4 v[114:117], v195, s[50:51] offset:1024
	v_add_u32_e32 v194, 0xc0000, v190
	v_pk_mul_f32 v[94:95], v[244:245], v[94:95] op_sel:[1,0] op_sel_hi:[1,1]
	v_pk_mul_f32 v[96:97], v[244:245], v[96:97] op_sel:[1,0] op_sel_hi:[1,1]
	v_pk_mul_f32 v[94:95], v[58:59], v[94:95]
	v_pk_mul_f32 v[96:97], v[60:61], v[96:97]
	v_mul_f32_e32 v94, v255, v94
	v_mul_f32_e32 v95, v255, v95
	v_mul_f32_e32 v96, v255, v96
	v_mul_f32_e32 v97, v255, v97
	v_exp_f32_e32 v94, v94
	v_exp_f32_e32 v95, v95
	v_exp_f32_e32 v96, v96
	v_exp_f32_e32 v97, v97
	v_add_f32_e32 v94, 1.0, v94
	v_add_f32_e32 v95, 1.0, v95
	v_add_f32_e32 v96, 1.0, v96
	v_add_f32_e32 v97, 1.0, v97
	v_rcp_f32_e32 v94, v94
	v_rcp_f32_e32 v95, v95
	v_rcp_f32_e32 v96, v96
	v_rcp_f32_e32 v97, v97
	s_waitcnt vmcnt(33)
	v_lshlrev_b32_e32 v250, 16, v162
	v_and_b32_e32 v251, 0xffff0000, v162
	v_lshlrev_b32_e32 v252, 16, v163
	v_and_b32_e32 v253, 0xffff0000, v163
	v_pk_fma_f32 v[146:147], v[94:95], v[250:251], v[146:147]
	v_pk_fma_f32 v[148:149], v[96:97], v[252:253], v[148:149]
	global_store_dwordx4 v194, v[146:149], s[54:55] offset:0
	v_pk_mul_f32 v[90:91], v[244:245], v[90:91] op_sel:[1,0] op_sel_hi:[1,1]
	v_pk_mul_f32 v[92:93], v[244:245], v[92:93] op_sel:[1,0] op_sel_hi:[1,1]
	v_pk_mul_f32 v[90:91], v[66:67], v[90:91]
	v_pk_mul_f32 v[92:93], v[68:69], v[92:93]
	v_mul_f32_e32 v90, v255, v90
	v_mul_f32_e32 v91, v255, v91
	v_mul_f32_e32 v92, v255, v92
	v_mul_f32_e32 v93, v255, v93
	v_exp_f32_e32 v90, v90
	v_exp_f32_e32 v91, v91
	v_exp_f32_e32 v92, v92
	v_exp_f32_e32 v93, v93
	v_add_f32_e32 v90, 1.0, v90
	v_add_f32_e32 v91, 1.0, v91
	v_add_f32_e32 v92, 1.0, v92
	v_add_f32_e32 v93, 1.0, v93
	v_rcp_f32_e32 v90, v90
	v_rcp_f32_e32 v91, v91
	v_rcp_f32_e32 v92, v92
	v_rcp_f32_e32 v93, v93
	v_lshlrev_b32_e32 v250, 16, v164
	v_and_b32_e32 v251, 0xffff0000, v164
	v_lshlrev_b32_e32 v252, 16, v165
	v_and_b32_e32 v253, 0xffff0000, v165
	v_pk_fma_f32 v[150:151], v[90:91], v[250:251], v[150:151]
	v_pk_fma_f32 v[152:153], v[92:93], v[252:253], v[152:153]
	global_store_dwordx4 v194, v[150:153], s[54:55] offset:64
	v_pk_mul_f32 v[86:87], v[244:245], v[86:87] op_sel:[1,0] op_sel_hi:[1,1]
	v_pk_mul_f32 v[88:89], v[244:245], v[88:89] op_sel:[1,0] op_sel_hi:[1,1]
	v_pk_mul_f32 v[86:87], v[74:75], v[86:87]
	v_pk_mul_f32 v[88:89], v[76:77], v[88:89]
	v_mul_f32_e32 v86, v255, v86
	v_mul_f32_e32 v87, v255, v87
	v_mul_f32_e32 v88, v255, v88
	v_mul_f32_e32 v89, v255, v89
	v_exp_f32_e32 v86, v86
	v_exp_f32_e32 v87, v87
	v_exp_f32_e32 v88, v88
	v_exp_f32_e32 v89, v89
	v_add_f32_e32 v86, 1.0, v86
	v_add_f32_e32 v87, 1.0, v87
	v_add_f32_e32 v88, 1.0, v88
	v_add_f32_e32 v89, 1.0, v89
	v_rcp_f32_e32 v86, v86
	v_rcp_f32_e32 v87, v87
	v_rcp_f32_e32 v88, v88
	v_rcp_f32_e32 v89, v89
	s_waitcnt vmcnt(34)
; __device__ __forceinline__ f32x4 sig4(const f32x4 v) { return (f32x4){sigmoidf_(v[0]), sigmoidf_(v[1]), sigmoidf_(v[2]), sigmoidf_(v[3])}; }
;     __device__ __forceinline__ void operator()(const typename AccT<I8>::type (&acc)[2][2][4][2], const Unit& u, int wr, int wc, int fr, int fq) const {
;     ...
;         for (int s = 0; s < 8; ++s) { const int ai = s >> 2, m = s & 3; const int r = row0 + ai * HALF + m * 16; const size_t off = (size_t)r * 4096 + col0;
;                 if (s + 1 < 8) load_row(nxt, (size_t)(row0 + ((s + 1) >> 2) * HALF + ((s + 1) & 3) * 16) * 4096 + col0);
;                 const float rs = rsv[s];
;                 float ss = 0.f, mx = 0.f;
; #pragma unroll
;                 for (int bj = 0; bj < 2; ++bj)
; #pragma unroll
;                     for (int n = 0; n < 2; ++n) { const size_t o = off + bj * HALF + n * 16; const f32x4 b = cur.b[bj][n]; f32x4 v;
;                         if constexpr (I8) v = __builtin_convertvector(acc[ai][bj][m][n], f32x4) * rs * sv[bj][n]; else v = acc[ai][bj][m][n];
;                         if (MODE == 1) { const u32x2 pw = cur.pw[bj][n]; const f32x4 pp = (f32x4){bf_lo(pw.x), bf_hi(pw.x), bf_lo(pw.y), bf_hi(pw.y)}; v = sig4(I8 ? v : v * rs) * pp; }
;                         const f32x4 x = b + v; *(f32x4*)(out + o) = x;
	v_lshlrev_b32_e32 v250, 16, v178
	v_and_b32_e32 v251, 0xffff0000, v178
	v_lshlrev_b32_e32 v252, 16, v179
	v_and_b32_e32 v253, 0xffff0000, v179
	v_pk_fma_f32 v[154:155], v[86:87], v[250:251], v[154:155]
	v_pk_fma_f32 v[156:157], v[88:89], v[252:253], v[156:157]
	global_store_dwordx4 v194, v[154:157], s[54:55] offset:512
	v_pk_mul_f32 v[82:83], v[244:245], v[82:83] op_sel:[1,0] op_sel_hi:[1,1]
	v_pk_mul_f32 v[84:85], v[244:245], v[84:85] op_sel:[1,0] op_sel_hi:[1,1]
	v_pk_mul_f32 v[82:83], v[78:79], v[82:83]
	v_pk_mul_f32 v[84:85], v[80:81], v[84:85]
	v_mul_f32_e32 v82, v255, v82
	v_mul_f32_e32 v83, v255, v83
	v_mul_f32_e32 v84, v255, v84
	v_mul_f32_e32 v85, v255, v85
	v_exp_f32_e32 v82, v82
	v_exp_f32_e32 v83, v83
	v_exp_f32_e32 v84, v84
	v_exp_f32_e32 v85, v85
	v_add_f32_e32 v82, 1.0, v82
	v_add_f32_e32 v83, 1.0, v83
	v_add_f32_e32 v84, 1.0, v84
	v_add_f32_e32 v85, 1.0, v85
	v_rcp_f32_e32 v82, v82
	v_rcp_f32_e32 v83, v83
	v_rcp_f32_e32 v84, v84
	v_rcp_f32_e32 v85, v85
	v_lshlrev_b32_e32 v250, 16, v180
	v_and_b32_e32 v251, 0xffff0000, v180
	v_lshlrev_b32_e32 v252, 16, v181
	v_and_b32_e32 v253, 0xffff0000, v181
	v_pk_fma_f32 v[158:159], v[82:83], v[250:251], v[158:159]
	v_pk_fma_f32 v[160:161], v[84:85], v[252:253], v[160:161]
	global_store_dwordx4 v194, v[158:161], s[54:55] offset:576
	v_add_u32_e32 v194, 0x200000, v190
	v_pk_mul_f32 v[70:71], v[246:247], v[70:71] op_sel:[0,0] op_sel_hi:[0,1]
	v_pk_mul_f32 v[72:73], v[246:247], v[72:73] op_sel:[0,0] op_sel_hi:[0,1]
	v_pk_mul_f32 v[70:71], v[58:59], v[70:71]
	v_pk_mul_f32 v[72:73], v[60:61], v[72:73]
	v_mul_f32_e32 v70, v255, v70
	v_mul_f32_e32 v71, v255, v71
	v_mul_f32_e32 v72, v255, v72
	v_mul_f32_e32 v73, v255, v73
	v_exp_f32_e32 v70, v70
	v_exp_f32_e32 v71, v71
	v_exp_f32_e32 v72, v72
	v_exp_f32_e32 v73, v73
	v_add_f32_e32 v70, 1.0, v70
	v_add_f32_e32 v71, 1.0, v71
	v_add_f32_e32 v72, 1.0, v72
	v_add_f32_e32 v73, 1.0, v73
	v_rcp_f32_e32 v70, v70
	v_rcp_f32_e32 v71, v71
	v_rcp_f32_e32 v72, v72
	v_rcp_f32_e32 v73, v73
	s_waitcnt vmcnt(27)
	v_lshlrev_b32_e32 v250, 16, v184
	v_and_b32_e32 v251, 0xffff0000, v184
	v_lshlrev_b32_e32 v252, 16, v185
	v_and_b32_e32 v253, 0xffff0000, v185
	v_pk_fma_f32 v[198:199], v[70:71], v[250:251], v[198:199]
	v_pk_fma_f32 v[200:201], v[72:73], v[252:253], v[200:201]
	global_store_dwordx4 v194, v[198:201], s[54:55] offset:0
	v_pk_mul_f32 v[62:63], v[246:247], v[62:63] op_sel:[0,0] op_sel_hi:[0,1]
	v_pk_mul_f32 v[64:65], v[246:247], v[64:65] op_sel:[0,0] op_sel_hi:[0,1]
	v_pk_mul_f32 v[62:63], v[66:67], v[62:63]
	v_pk_mul_f32 v[64:65], v[68:69], v[64:65]
	v_mul_f32_e32 v62, v255, v62
	v_mul_f32_e32 v63, v255, v63
	v_mul_f32_e32 v64, v255, v64
	v_mul_f32_e32 v65, v255, v65
	v_exp_f32_e32 v62, v62
	v_exp_f32_e32 v63, v63
	v_exp_f32_e32 v64, v64
	v_exp_f32_e32 v65, v65
	v_add_f32_e32 v62, 1.0, v62
	v_add_f32_e32 v63, 1.0, v63
	v_add_f32_e32 v64, 1.0, v64
	v_add_f32_e32 v65, 1.0, v65
	v_rcp_f32_e32 v62, v62
	v_rcp_f32_e32 v63, v63
	v_rcp_f32_e32 v64, v64
	v_rcp_f32_e32 v65, v65
	v_lshlrev_b32_e32 v250, 16, v186
	v_and_b32_e32 v251, 0xffff0000, v186
	v_lshlrev_b32_e32 v252, 16, v187
	v_and_b32_e32 v253, 0xffff0000, v187
	v_pk_fma_f32 v[202:203], v[62:63], v[250:251], v[202:203]
	v_pk_fma_f32 v[204:205], v[64:65], v[252:253], v[204:205]
	global_store_dwordx4 v194, v[202:205], s[54:55] offset:64
	v_pk_mul_f32 v[54:55], v[246:247], v[54:55] op_sel:[0,0] op_sel_hi:[0,1]
	v_pk_mul_f32 v[56:57], v[246:247], v[56:57] op_sel:[0,0] op_sel_hi:[0,1]
	v_pk_mul_f32 v[54:55], v[74:75], v[54:55]
	v_pk_mul_f32 v[56:57], v[76:77], v[56:57]
	v_mul_f32_e32 v54, v255, v54
	v_mul_f32_e32 v55, v255, v55
	v_mul_f32_e32 v56, v255, v56
	v_mul_f32_e32 v57, v255, v57
	v_exp_f32_e32 v54, v54
	v_exp_f32_e32 v55, v55
	v_exp_f32_e32 v56, v56
	v_exp_f32_e32 v57, v57
	v_add_f32_e32 v54, 1.0, v54
	v_add_f32_e32 v55, 1.0, v55
	v_add_f32_e32 v56, 1.0, v56
	v_add_f32_e32 v57, 1.0, v57
	v_rcp_f32_e32 v54, v54
	v_rcp_f32_e32 v55, v55
	v_rcp_f32_e32 v56, v56
	v_rcp_f32_e32 v57, v57
	s_waitcnt vmcnt(28)
	v_lshlrev_b32_e32 v250, 16, v214
	v_and_b32_e32 v251, 0xffff0000, v214
	v_lshlrev_b32_e32 v252, 16, v215
	v_and_b32_e32 v253, 0xffff0000, v215
	v_pk_fma_f32 v[206:207], v[54:55], v[250:251], v[206:207]
	v_pk_fma_f32 v[208:209], v[56:57], v[252:253], v[208:209]
	global_store_dwordx4 v194, v[206:209], s[54:55] offset:512
	v_pk_mul_f32 v[50:51], v[246:247], v[50:51] op_sel:[0,0] op_sel_hi:[0,1]
	v_pk_mul_f32 v[52:53], v[246:247], v[52:53] op_sel:[0,0] op_sel_hi:[0,1]
	v_pk_mul_f32 v[50:51], v[78:79], v[50:51]
	v_pk_mul_f32 v[52:53], v[80:81], v[52:53]
	v_mul_f32_e32 v50, v255, v50
	v_mul_f32_e32 v51, v255, v51
	v_mul_f32_e32 v52, v255, v52
	v_mul_f32_e32 v53, v255, v53
	v_exp_f32_e32 v50, v50
	v_exp_f32_e32 v51, v51
	v_exp_f32_e32 v52, v52
	v_exp_f32_e32 v53, v53
	v_add_f32_e32 v50, 1.0, v50
	v_add_f32_e32 v51, 1.0, v51
	v_add_f32_e32 v52, 1.0, v52
	v_add_f32_e32 v53, 1.0, v53
	v_rcp_f32_e32 v50, v50
	v_rcp_f32_e32 v51, v51
	v_rcp_f32_e32 v52, v52
	v_rcp_f32_e32 v53, v53
	v_lshlrev_b32_e32 v250, 16, v216
	v_and_b32_e32 v251, 0xffff0000, v216
	v_lshlrev_b32_e32 v252, 16, v217
	v_and_b32_e32 v253, 0xffff0000, v217
	v_pk_fma_f32 v[210:211], v[50:51], v[250:251], v[210:211]
	v_pk_fma_f32 v[212:213], v[52:53], v[252:253], v[212:213]
	global_store_dwordx4 v194, v[210:213], s[54:55] offset:576
	v_add_u32_e32 v194, 0x240000, v190
	v_pk_mul_f32 v[46:47], v[246:247], v[46:47] op_sel:[1,0] op_sel_hi:[1,1]
	v_pk_mul_f32 v[48:49], v[246:247], v[48:49] op_sel:[1,0] op_sel_hi:[1,1]
	v_pk_mul_f32 v[46:47], v[58:59], v[46:47]
	v_pk_mul_f32 v[48:49], v[60:61], v[48:49]
	v_mul_f32_e32 v46, v255, v46
	v_mul_f32_e32 v47, v255, v47
	v_mul_f32_e32 v48, v255, v48
	v_mul_f32_e32 v49, v255, v49
	v_exp_f32_e32 v46, v46
	v_exp_f32_e32 v47, v47
	v_exp_f32_e32 v48, v48
	v_exp_f32_e32 v49, v49
	v_add_f32_e32 v46, 1.0, v46
	v_add_f32_e32 v47, 1.0, v47
	v_add_f32_e32 v48, 1.0, v48
	v_add_f32_e32 v49, 1.0, v49
	v_rcp_f32_e32 v46, v46
	v_rcp_f32_e32 v47, v47
	v_rcp_f32_e32 v48, v48
	v_rcp_f32_e32 v49, v49
	s_waitcnt vmcnt(25)
; __device__ __forceinline__ f32x4 sig4(const f32x4 v) { return (f32x4){sigmoidf_(v[0]), sigmoidf_(v[1]), sigmoidf_(v[2]), sigmoidf_(v[3])}; }
;     __device__ __forceinline__ void operator()(const typename AccT<I8>::type (&acc)[2][2][4][2], const Unit& u, int wr, int wc, int fr, int fq) const {
;     ...
;         for (int s = 0; s < 8; ++s) { const int ai = s >> 2, m = s & 3; const int r = row0 + ai * HALF + m * 16; const size_t off = (size_t)r * 4096 + col0;
;                 if (s + 1 < 8) load_row(nxt, (size_t)(row0 + ((s + 1) >> 2) * HALF + ((s + 1) & 3) * 16) * 4096 + col0);
;                 const float rs = rsv[s];
;                 float ss = 0.f, mx = 0.f;
; #pragma unroll
;                 for (int bj = 0; bj < 2; ++bj)
; #pragma unroll
;                     for (int n = 0; n < 2; ++n) { const size_t o = off + bj * HALF + n * 16; const f32x4 b = cur.b[bj][n]; f32x4 v;
;                         if constexpr (I8) v = __builtin_convertvector(acc[ai][bj][m][n], f32x4) * rs * sv[bj][n]; else v = acc[ai][bj][m][n];
;                         if (MODE == 1) { const u32x2 pw = cur.pw[bj][n]; const f32x4 pp = (f32x4){bf_lo(pw.x), bf_hi(pw.x), bf_lo(pw.y), bf_hi(pw.y)}; v = sig4(I8 ? v : v * rs) * pp; }
;                         const f32x4 x = b + v; *(f32x4*)(out + o) = x;
	v_lshlrev_b32_e32 v250, 16, v126
	v_and_b32_e32 v251, 0xffff0000, v126
	v_lshlrev_b32_e32 v252, 16, v127
	v_and_b32_e32 v253, 0xffff0000, v127
	v_pk_fma_f32 v[142:143], v[46:47], v[250:251], v[142:143]
	v_pk_fma_f32 v[144:145], v[48:49], v[252:253], v[144:145]
	global_store_dwordx4 v194, v[142:145], s[54:55] offset:0
	v_pk_mul_f32 v[42:43], v[246:247], v[42:43] op_sel:[1,0] op_sel_hi:[1,1]
	v_pk_mul_f32 v[44:45], v[246:247], v[44:45] op_sel:[1,0] op_sel_hi:[1,1]
	v_pk_mul_f32 v[42:43], v[66:67], v[42:43]
	v_pk_mul_f32 v[44:45], v[68:69], v[44:45]
	v_mul_f32_e32 v42, v255, v42
	v_mul_f32_e32 v43, v255, v43
	v_mul_f32_e32 v44, v255, v44
	v_mul_f32_e32 v45, v255, v45
	v_exp_f32_e32 v42, v42
	v_exp_f32_e32 v43, v43
	v_exp_f32_e32 v44, v44
	v_exp_f32_e32 v45, v45
	v_add_f32_e32 v42, 1.0, v42
	v_add_f32_e32 v43, 1.0, v43
	v_add_f32_e32 v44, 1.0, v44
	v_add_f32_e32 v45, 1.0, v45
	v_rcp_f32_e32 v42, v42
	v_rcp_f32_e32 v43, v43
	v_rcp_f32_e32 v44, v44
	v_rcp_f32_e32 v45, v45
	v_lshlrev_b32_e32 v250, 16, v128
	v_and_b32_e32 v251, 0xffff0000, v128
	v_lshlrev_b32_e32 v252, 16, v129
	v_and_b32_e32 v253, 0xffff0000, v129
	v_pk_fma_f32 v[138:139], v[42:43], v[250:251], v[138:139]
	v_pk_fma_f32 v[140:141], v[44:45], v[252:253], v[140:141]
	global_store_dwordx4 v194, v[138:141], s[54:55] offset:64
	v_pk_mul_f32 v[38:39], v[246:247], v[38:39] op_sel:[1,0] op_sel_hi:[1,1]
	v_pk_mul_f32 v[40:41], v[246:247], v[40:41] op_sel:[1,0] op_sel_hi:[1,1]
	v_pk_mul_f32 v[38:39], v[74:75], v[38:39]
	v_pk_mul_f32 v[40:41], v[76:77], v[40:41]
	v_mul_f32_e32 v38, v255, v38
	v_mul_f32_e32 v39, v255, v39
	v_mul_f32_e32 v40, v255, v40
	v_mul_f32_e32 v41, v255, v41
	v_exp_f32_e32 v38, v38
	v_exp_f32_e32 v39, v39
	v_exp_f32_e32 v40, v40
	v_exp_f32_e32 v41, v41
	v_add_f32_e32 v38, 1.0, v38
	v_add_f32_e32 v39, 1.0, v39
	v_add_f32_e32 v40, 1.0, v40
	v_add_f32_e32 v41, 1.0, v41
	v_rcp_f32_e32 v38, v38
	v_rcp_f32_e32 v39, v39
	v_rcp_f32_e32 v40, v40
	v_rcp_f32_e32 v41, v41
	s_waitcnt vmcnt(26)
	v_lshlrev_b32_e32 v250, 16, v122
	v_and_b32_e32 v251, 0xffff0000, v122
	v_lshlrev_b32_e32 v252, 16, v123
	v_and_b32_e32 v253, 0xffff0000, v123
	v_pk_fma_f32 v[134:135], v[38:39], v[250:251], v[134:135]
	v_pk_fma_f32 v[136:137], v[40:41], v[252:253], v[136:137]
	global_store_dwordx4 v194, v[134:137], s[54:55] offset:512
	v_pk_mul_f32 v[34:35], v[246:247], v[34:35] op_sel:[1,0] op_sel_hi:[1,1]
	v_pk_mul_f32 v[36:37], v[246:247], v[36:37] op_sel:[1,0] op_sel_hi:[1,1]
	v_pk_mul_f32 v[34:35], v[78:79], v[34:35]
	v_pk_mul_f32 v[36:37], v[80:81], v[36:37]
	v_mul_f32_e32 v34, v255, v34
	v_mul_f32_e32 v35, v255, v35
	v_mul_f32_e32 v36, v255, v36
	v_mul_f32_e32 v37, v255, v37
	v_exp_f32_e32 v34, v34
	v_exp_f32_e32 v35, v35
	v_exp_f32_e32 v36, v36
	v_exp_f32_e32 v37, v37
	v_add_f32_e32 v34, 1.0, v34
	v_add_f32_e32 v35, 1.0, v35
	v_add_f32_e32 v36, 1.0, v36
	v_add_f32_e32 v37, 1.0, v37
	v_rcp_f32_e32 v34, v34
	v_rcp_f32_e32 v35, v35
	v_rcp_f32_e32 v36, v36
	v_rcp_f32_e32 v37, v37
	v_lshlrev_b32_e32 v250, 16, v124
	v_and_b32_e32 v251, 0xffff0000, v124
	v_lshlrev_b32_e32 v252, 16, v125
	v_and_b32_e32 v253, 0xffff0000, v125
	v_pk_fma_f32 v[130:131], v[34:35], v[250:251], v[130:131]
	v_pk_fma_f32 v[132:133], v[36:37], v[252:253], v[132:133]
	global_store_dwordx4 v194, v[130:133], s[54:55] offset:576
	v_add_u32_e32 v194, 0x280000, v190
	v_pk_mul_f32 v[30:31], v[248:249], v[30:31] op_sel:[0,0] op_sel_hi:[0,1]
	v_pk_mul_f32 v[32:33], v[248:249], v[32:33] op_sel:[0,0] op_sel_hi:[0,1]
	v_pk_mul_f32 v[30:31], v[58:59], v[30:31]
	v_pk_mul_f32 v[32:33], v[60:61], v[32:33]
	v_mul_f32_e32 v30, v255, v30
	v_mul_f32_e32 v31, v255, v31
	v_mul_f32_e32 v32, v255, v32
	v_mul_f32_e32 v33, v255, v33
	v_exp_f32_e32 v30, v30
	v_exp_f32_e32 v31, v31
	v_exp_f32_e32 v32, v32
	v_exp_f32_e32 v33, v33
	v_add_f32_e32 v30, 1.0, v30
	v_add_f32_e32 v31, 1.0, v31
	v_add_f32_e32 v32, 1.0, v32
	v_add_f32_e32 v33, 1.0, v33
	v_rcp_f32_e32 v30, v30
	v_rcp_f32_e32 v31, v31
	v_rcp_f32_e32 v32, v32
	v_rcp_f32_e32 v33, v33
	s_waitcnt vmcnt(19)
	v_lshlrev_b32_e32 v250, 16, v234
	v_and_b32_e32 v251, 0xffff0000, v234
	v_lshlrev_b32_e32 v252, 16, v235
	v_and_b32_e32 v253, 0xffff0000, v235
	v_pk_fma_f32 v[218:219], v[30:31], v[250:251], v[218:219]
	v_pk_fma_f32 v[220:221], v[32:33], v[252:253], v[220:221]
	global_store_dwordx4 v194, v[218:221], s[54:55] offset:0
	v_pk_mul_f32 v[26:27], v[248:249], v[26:27] op_sel:[0,0] op_sel_hi:[0,1]
	v_pk_mul_f32 v[28:29], v[248:249], v[28:29] op_sel:[0,0] op_sel_hi:[0,1]
	v_pk_mul_f32 v[26:27], v[66:67], v[26:27]
	v_pk_mul_f32 v[28:29], v[68:69], v[28:29]
	v_mul_f32_e32 v26, v255, v26
	v_mul_f32_e32 v27, v255, v27
	v_mul_f32_e32 v28, v255, v28
	v_mul_f32_e32 v29, v255, v29
	v_exp_f32_e32 v26, v26
	v_exp_f32_e32 v27, v27
	v_exp_f32_e32 v28, v28
	v_exp_f32_e32 v29, v29
	v_add_f32_e32 v26, 1.0, v26
	v_add_f32_e32 v27, 1.0, v27
	v_add_f32_e32 v28, 1.0, v28
	v_add_f32_e32 v29, 1.0, v29
	v_rcp_f32_e32 v26, v26
	v_rcp_f32_e32 v27, v27
	v_rcp_f32_e32 v28, v28
	v_rcp_f32_e32 v29, v29
	v_lshlrev_b32_e32 v250, 16, v236
	v_and_b32_e32 v251, 0xffff0000, v236
	v_lshlrev_b32_e32 v252, 16, v237
	v_and_b32_e32 v253, 0xffff0000, v237
	v_pk_fma_f32 v[222:223], v[26:27], v[250:251], v[222:223]
	v_pk_fma_f32 v[224:225], v[28:29], v[252:253], v[224:225]
	global_store_dwordx4 v194, v[222:225], s[54:55] offset:64
	v_pk_mul_f32 v[22:23], v[248:249], v[22:23] op_sel:[0,0] op_sel_hi:[0,1]
	v_pk_mul_f32 v[24:25], v[248:249], v[24:25] op_sel:[0,0] op_sel_hi:[0,1]
	v_pk_mul_f32 v[22:23], v[74:75], v[22:23]
	v_pk_mul_f32 v[24:25], v[76:77], v[24:25]
	v_mul_f32_e32 v22, v255, v22
	v_mul_f32_e32 v23, v255, v23
	v_mul_f32_e32 v24, v255, v24
	v_mul_f32_e32 v25, v255, v25
	v_exp_f32_e32 v22, v22
	v_exp_f32_e32 v23, v23
	v_exp_f32_e32 v24, v24
	v_exp_f32_e32 v25, v25
	v_add_f32_e32 v22, 1.0, v22
	v_add_f32_e32 v23, 1.0, v23
	v_add_f32_e32 v24, 1.0, v24
	v_add_f32_e32 v25, 1.0, v25
	v_rcp_f32_e32 v22, v22
	v_rcp_f32_e32 v23, v23
	v_rcp_f32_e32 v24, v24
	v_rcp_f32_e32 v25, v25
	s_waitcnt vmcnt(20)
; #define PG8_BAR __builtin_amdgcn_s_barrier()
; __device__ __forceinline__ f32x4 sig4(const f32x4 v) { return (f32x4){sigmoidf_(v[0]), sigmoidf_(v[1]), sigmoidf_(v[2]), sigmoidf_(v[3])}; }
; template <class Epi, class Sched, bool ALIGN_EPI = false, bool SP2 = false, bool I8 = false>
; __device__ __forceinline__ void gemm_phase(PG8_LAS unsigned char* lds, const Gemm g, const Sched& S, const Epi& E) {
;     ...
;         if (!has_next) break;
; #pragma unroll
;         for (int a = 0; a < 2; ++a)
; #pragma unroll
;             for (int b = 0; b < 2; ++b)
; #pragma unroll
;                 for (int m = 0; m < 4; ++m)
; #pragma unroll
;                     for (int n = 0; n < 2; ++n) acc[a][b][m][n] = (typename AccT<I8>::type){0, 0, 0, 0};
;         cur = nxt; cA = nA; cB = nB; ++ui; nt = PG8_NT(cur);
;         if constexpr (ALIGN_EPI) { if (wr == 1) PG8_BAR; }
;     __device__ __forceinline__ void operator()(const typename AccT<I8>::type (&acc)[2][2][4][2], const Unit& u, int wr, int wc, int fr, int fq) const {
;     ...
;                     for (int n = 0; n < 2; ++n) { const size_t o = off + bj * HALF + n * 16; const f32x4 b = cur.b[bj][n]; f32x4 v;
;                         if constexpr (I8) v = __builtin_convertvector(acc[ai][bj][m][n], f32x4) * rs * sv[bj][n]; else v = acc[ai][bj][m][n];
;                         if (MODE == 1) { const u32x2 pw = cur.pw[bj][n]; const f32x4 pp = (f32x4){bf_lo(pw.x), bf_hi(pw.x), bf_lo(pw.y), bf_hi(pw.y)}; v = sig4(I8 ? v : v * rs) * pp; }
;                         const f32x4 x = b + v; *(f32x4*)(out + o) = x;
	v_lshlrev_b32_e32 v250, 16, v238
	v_and_b32_e32 v251, 0xffff0000, v238
	v_lshlrev_b32_e32 v252, 16, v239
	v_and_b32_e32 v253, 0xffff0000, v239
	v_pk_fma_f32 v[226:227], v[22:23], v[250:251], v[226:227]
	v_pk_fma_f32 v[228:229], v[24:25], v[252:253], v[228:229]
	global_store_dwordx4 v194, v[226:229], s[54:55] offset:512
	v_pk_mul_f32 v[18:19], v[248:249], v[18:19] op_sel:[0,0] op_sel_hi:[0,1]
	v_pk_mul_f32 v[20:21], v[248:249], v[20:21] op_sel:[0,0] op_sel_hi:[0,1]
	v_pk_mul_f32 v[18:19], v[78:79], v[18:19]
	v_pk_mul_f32 v[20:21], v[80:81], v[20:21]
	v_mul_f32_e32 v18, v255, v18
	v_mul_f32_e32 v19, v255, v19
	v_mul_f32_e32 v20, v255, v20
	v_mul_f32_e32 v21, v255, v21
	v_exp_f32_e32 v18, v18
	v_exp_f32_e32 v19, v19
	v_exp_f32_e32 v20, v20
	v_exp_f32_e32 v21, v21
	v_add_f32_e32 v18, 1.0, v18
	v_add_f32_e32 v19, 1.0, v19
	v_add_f32_e32 v20, 1.0, v20
	v_add_f32_e32 v21, 1.0, v21
	v_rcp_f32_e32 v18, v18
	v_rcp_f32_e32 v19, v19
	v_rcp_f32_e32 v20, v20
	v_rcp_f32_e32 v21, v21
	v_lshlrev_b32_e32 v250, 16, v240
	v_and_b32_e32 v251, 0xffff0000, v240
	v_lshlrev_b32_e32 v252, 16, v241
	v_and_b32_e32 v253, 0xffff0000, v241
	v_pk_fma_f32 v[230:231], v[18:19], v[250:251], v[230:231]
	v_pk_fma_f32 v[232:233], v[20:21], v[252:253], v[232:233]
	global_store_dwordx4 v194, v[230:233], s[54:55] offset:576
	v_add_u32_e32 v194, 0x2c0000, v190
	v_pk_mul_f32 v[14:15], v[248:249], v[14:15] op_sel:[1,0] op_sel_hi:[1,1]
	v_pk_mul_f32 v[16:17], v[248:249], v[16:17] op_sel:[1,0] op_sel_hi:[1,1]
	v_pk_mul_f32 v[14:15], v[58:59], v[14:15]
	v_pk_mul_f32 v[16:17], v[60:61], v[16:17]
	v_mul_f32_e32 v14, v255, v14
	v_mul_f32_e32 v15, v255, v15
	v_mul_f32_e32 v16, v255, v16
	v_mul_f32_e32 v17, v255, v17
	v_exp_f32_e32 v14, v14
	v_exp_f32_e32 v15, v15
	v_exp_f32_e32 v16, v16
	v_exp_f32_e32 v17, v17
	v_add_f32_e32 v14, 1.0, v14
	v_add_f32_e32 v15, 1.0, v15
	v_add_f32_e32 v16, 1.0, v16
	v_add_f32_e32 v17, 1.0, v17
	v_rcp_f32_e32 v14, v14
	v_rcp_f32_e32 v15, v15
	v_rcp_f32_e32 v16, v16
	v_rcp_f32_e32 v17, v17
	s_waitcnt vmcnt(17)
	v_lshlrev_b32_e32 v250, 16, v118
	v_and_b32_e32 v251, 0xffff0000, v118
	v_lshlrev_b32_e32 v252, 16, v119
	v_and_b32_e32 v253, 0xffff0000, v119
	v_pk_fma_f32 v[110:111], v[14:15], v[250:251], v[110:111]
	v_pk_fma_f32 v[112:113], v[16:17], v[252:253], v[112:113]
	global_store_dwordx4 v194, v[110:113], s[54:55] offset:0
	v_pk_mul_f32 v[10:11], v[248:249], v[10:11] op_sel:[1,0] op_sel_hi:[1,1]
	v_pk_mul_f32 v[12:13], v[248:249], v[12:13] op_sel:[1,0] op_sel_hi:[1,1]
	v_pk_mul_f32 v[10:11], v[66:67], v[10:11]
	v_pk_mul_f32 v[12:13], v[68:69], v[12:13]
	v_mul_f32_e32 v10, v255, v10
	v_mul_f32_e32 v11, v255, v11
	v_mul_f32_e32 v12, v255, v12
	v_mul_f32_e32 v13, v255, v13
	v_exp_f32_e32 v10, v10
	v_exp_f32_e32 v11, v11
	v_exp_f32_e32 v12, v12
	v_exp_f32_e32 v13, v13
	v_add_f32_e32 v10, 1.0, v10
	v_add_f32_e32 v11, 1.0, v11
	v_add_f32_e32 v12, 1.0, v12
	v_add_f32_e32 v13, 1.0, v13
	v_rcp_f32_e32 v10, v10
	v_rcp_f32_e32 v11, v11
	v_rcp_f32_e32 v12, v12
	v_rcp_f32_e32 v13, v13
	v_lshlrev_b32_e32 v250, 16, v120
	v_and_b32_e32 v251, 0xffff0000, v120
	v_lshlrev_b32_e32 v252, 16, v121
	v_and_b32_e32 v253, 0xffff0000, v121
	v_pk_fma_f32 v[106:107], v[10:11], v[250:251], v[106:107]
	v_pk_fma_f32 v[108:109], v[12:13], v[252:253], v[108:109]
	global_store_dwordx4 v194, v[106:109], s[54:55] offset:64
	v_pk_mul_f32 v[6:7], v[248:249], v[6:7] op_sel:[1,0] op_sel_hi:[1,1]
	v_pk_mul_f32 v[8:9], v[248:249], v[8:9] op_sel:[1,0] op_sel_hi:[1,1]
	v_pk_mul_f32 v[6:7], v[74:75], v[6:7]
	v_pk_mul_f32 v[8:9], v[76:77], v[8:9]
	v_mul_f32_e32 v6, v255, v6
	v_mul_f32_e32 v7, v255, v7
	v_mul_f32_e32 v8, v255, v8
	v_mul_f32_e32 v9, v255, v9
	v_exp_f32_e32 v6, v6
	v_exp_f32_e32 v7, v7
	v_exp_f32_e32 v8, v8
	v_exp_f32_e32 v9, v9
	v_add_f32_e32 v6, 1.0, v6
	v_add_f32_e32 v7, 1.0, v7
	v_add_f32_e32 v8, 1.0, v8
	v_add_f32_e32 v9, 1.0, v9
	v_rcp_f32_e32 v6, v6
	v_rcp_f32_e32 v7, v7
	v_rcp_f32_e32 v8, v8
	v_rcp_f32_e32 v9, v9
	s_waitcnt vmcnt(18)
	v_lshlrev_b32_e32 v250, 16, v114
	v_and_b32_e32 v251, 0xffff0000, v114
	v_lshlrev_b32_e32 v252, 16, v115
	v_and_b32_e32 v253, 0xffff0000, v115
	v_pk_fma_f32 v[102:103], v[6:7], v[250:251], v[102:103]
	v_pk_fma_f32 v[104:105], v[8:9], v[252:253], v[104:105]
	global_store_dwordx4 v194, v[102:105], s[54:55] offset:512
	v_pk_mul_f32 v[2:3], v[248:249], v[2:3] op_sel:[1,0] op_sel_hi:[1,1]
	v_pk_mul_f32 v[4:5], v[248:249], v[4:5] op_sel:[1,0] op_sel_hi:[1,1]
	v_pk_mul_f32 v[2:3], v[78:79], v[2:3]
	v_pk_mul_f32 v[4:5], v[80:81], v[4:5]
	v_mul_f32_e32 v2, v255, v2
	v_mul_f32_e32 v3, v255, v3
	v_mul_f32_e32 v4, v255, v4
	v_mul_f32_e32 v5, v255, v5
	v_exp_f32_e32 v2, v2
	v_exp_f32_e32 v3, v3
	v_exp_f32_e32 v4, v4
	v_exp_f32_e32 v5, v5
	v_add_f32_e32 v2, 1.0, v2
	v_add_f32_e32 v3, 1.0, v3
	v_add_f32_e32 v4, 1.0, v4
	v_add_f32_e32 v5, 1.0, v5
	v_rcp_f32_e32 v2, v2
	v_rcp_f32_e32 v3, v3
	v_rcp_f32_e32 v4, v4
	v_rcp_f32_e32 v5, v5
	v_lshlrev_b32_e32 v250, 16, v116
	v_and_b32_e32 v251, 0xffff0000, v116
	v_lshlrev_b32_e32 v252, 16, v117
	v_and_b32_e32 v253, 0xffff0000, v117
	v_pk_fma_f32 v[98:99], v[2:3], v[250:251], v[98:99]
	v_pk_fma_f32 v[100:101], v[4:5], v[252:253], v[100:101]
	global_store_dwordx4 v194, v[98:101], s[54:55] offset:576
	v_readlane_b32 s48, v254, 8
	s_mov_b64 s[26:27], s[54:55]
	s_andn2_b64 vcc, exec, s[0:1]
	s_mov_b64 s[0:1], -1
	v_readlane_b32 s49, v254, 9
	v_readlane_b32 s50, v254, 10
	v_readlane_b32 s51, v254, 11
	v_readlane_b32 s52, v254, 12
	v_readlane_b32 s53, v254, 13
	s_cbranch_vccnz .LBB0_2314
	s_andn2_b64 vcc, exec, s[4:5]
	s_cbranch_vccnz .LBB0_2313
	s_barrier
	s_branch .LBB0_2313
